# attention chunk loops (static mixer-A part and stick-breaking): K/V prefetch loads converted flat->global and the vmcnt(0) right after issuing the next chunk's loads replaced by counted vmcnt(8), so t
# speedup vs baseline: 1.0019x; 1.0019x over previous
; __device__ __forceinline__ void load_q(bf16x8 (&qf)[4], const bf16_t* qrow, int h) {
; #pragma unroll
;     for (int ks = 0; ks < 4; ++ks) qf[ks] = *(const bf16x8*)(qrow + 16 * ks + 8 * h);
; }
; template <bool CLAMP>
; __device__ __forceinline__ void load_k(bf16x8 (&kf)[4], const bf16_t* kbase, int k0, int kst, const WaveCtx& c) {
;     int kp = k0 + kst * c.q; if (CLAMP) kp = kp < 0 ? 0 : (kp > SEQ - 1 ? SEQ - 1 : kp);
;     const bf16_t* kr = kbase + (size_t)kp * LDQ + 8 * c.h;
; #pragma unroll
;     for (int ks = 0; ks < 4; ++ks) kf[ks] = *(const bf16x8*)(kr + 16 * ks);
; }
; template <bool CLAMP>
; __device__ __forceinline__ void load_v(u32x4 (&vr)[4], const bf16_t* vbase, int k0, int kst, const WaveCtx& c) {
; #pragma unroll
;     for (int i = 0; i < 4; ++i) { const int p = c.lane + 64 * i, n = p >> 3; int kp = k0 + kst * n; if (CLAMP) kp = kp < 0 ? 0 : (kp > SEQ - 1 ? SEQ - 1 : kp);
;         vr[i] = *(const u32x4*)(vbase + (size_t)kp * LDQ + (p & 7) * 8); }
; __device__ __forceinline__ void unit_A2(const bf16_t* qkv, bf16_t* outA, int b, int slot, int blk, int w, LAS unsigned char* lds, const WaveCtx& c) {
;     ...
;         const int qp1 = 256 * blk + 32 * w + c.q, head = slot;
;         bf16x8 qf[4]; load_q(qf, rowb + (size_t)qp1 * LDQ + head * 64, c.h);
;         const bf16_t* kbase = rowb + MIXW + head * 64; const bf16_t* vbase = rowb + 2 * MIXW + head * 64;
;         int ks0 = 256 * blk + 32 * w - 128; if (ks0 < 0) ks0 = 0;
;         const int ntot = ((256 * blk + 32 * w + 31 - ks0) + 1 + 31) >> 5;
;         KV ta, tb;
;         issue_kv<true>(ta, kbase, vbase, ks0, 1, c);
;         for (int i = 0; i < ntot; i += 2) {
;             if (i + 1 < ntot) issue_kv<true>(tb, kbase, vbase, ks0 + 32 * (i + 1), 1, c);
.LBB0_393:
	s_mov_b32 s46, 0
	s_andn2_b64 vcc, exec, s[0:1]
	s_mul_i32 s29, s77, 0x1200
	s_cbranch_vccnz .LBB0_440
	v_readlane_b32 s0, v255, 7
	s_add_u32 s2, s84, s0
	s_addc_u32 s3, s85, 0
	s_add_u32 s10, s2, 0x1800
	s_addc_u32 s11, s3, 0
	v_mov_b32_e32 v0, v236
	s_lshl_b32 s34, s77, 5
	s_add_i32 s1, s34, s78
	v_and_b32_e32 v217, 63, v0
	v_and_b32_e32 v214, 31, v0
	v_bfe_u32 v219, v0, 5, 1
	v_lshrrev_b32_e32 v218, 2, v0
	v_and_b32_e32 v1, 16, v0
	v_lshlrev_b32_e32 v0, 2, v0
	s_max_i32 s0, s1, 0x80
	v_lshlrev_b32_e32 v213, 2, v219
	v_and_or_b32 v0, v0, 12, v1
	s_sub_i32 s4, s1, s0
	v_and_or_b32 v2, v218, 3, v213
	v_lshlrev_b32_e32 v0, 1, v0
	s_addk_i32 s4, 0xbf
	s_add_i32 s12, s29, 0
	v_mad_u32_u24 v215, v2, s58, v0
	v_lshlrev_b32_e32 v0, 3, v219
	s_ashr_i32 s7, s4, 5
	v_lshlrev_b32_e32 v1, 4, v217
	s_cmp_lt_i32 s7, 1
	v_lshrrev_b32_e32 v216, 3, v217
	v_lshlrev_b32_e32 v194, 1, v0
	v_and_b32_e32 v196, 0x70, v1
	s_cbranch_scc1 .LBB0_414
	v_readlane_b32 s4, v254, 27
	v_readlane_b32 s5, v254, 28
	s_lshl_b64 s[4:5], s[4:5], 1
	s_add_u32 s8, s2, s4
	s_addc_u32 s9, s3, s5
	v_or_b32_e32 v2, s1, v214
	v_mov_b64_e32 v[0:1], s[8:9]
	v_mad_i64_i32 v[0:1], s[14:15], v2, s71, v[0:1]
	v_mov_b32_e32 v195, v65
	s_add_i32 s1, s0, 0xffffff80
	v_lshl_add_u64 v[0:1], v[0:1], 0, v[194:195]
	v_or_b32_e32 v4, s1, v216
	s_waitcnt vmcnt(0)
	global_load_dwordx4 v[98:101], v[0:1], off
	global_load_dwordx4 v[102:105], v[0:1], off offset:32
	global_load_dwordx4 v[106:109], v[0:1], off offset:64
	global_load_dwordx4 v[110:113], v[0:1], off offset:96
	v_or_b32_e32 v0, 24, v4
	v_min_u32_e32 v0, 0x7ff, v0
	v_or_b32_e32 v2, 16, v4
	s_add_u32 s4, s10, s4
	v_mul_u32_u24_e32 v0, 0x1200, v0
	v_min_u32_e32 v2, 0x7ff, v2
	s_addc_u32 s5, s11, s5
	v_lshlrev_b32_e32 v64, 1, v0
	v_mul_u32_u24_e32 v2, 0x1200, v2
	v_lshl_add_u64 v[0:1], s[4:5], 0, v[64:65]
	v_mov_b32_e32 v197, v65
	v_lshlrev_b32_e32 v64, 1, v2
	v_lshl_add_u64 v[0:1], v[0:1], 0, v[196:197]
	s_waitcnt lgkmcnt(0)
	v_lshl_add_u64 v[2:3], s[4:5], 0, v[64:65]
	v_lshl_add_u64 v[2:3], v[2:3], 0, v[196:197]
	global_load_dwordx4 v[134:137], v[0:1], off
	global_load_dwordx4 v[130:133], v[2:3], off
	v_or_b32_e32 v0, 8, v4
	v_min_u32_e32 v0, 0x7ff, v0
	v_mul_u32_u24_e32 v0, 0x1200, v0
	v_min_u32_e32 v2, 0x7ff, v4
	v_lshlrev_b32_e32 v64, 1, v0
	v_mul_u32_u24_e32 v2, 0x1200, v2
	v_lshl_add_u64 v[0:1], s[4:5], 0, v[64:65]
	v_lshlrev_b32_e32 v64, 1, v2
	v_lshl_add_u64 v[0:1], v[0:1], 0, v[196:197]
	v_lshl_add_u64 v[2:3], s[4:5], 0, v[64:65]
	v_lshl_add_u64 v[2:3], v[2:3], 0, v[196:197]
	global_load_dwordx4 v[142:145], v[0:1], off
	global_load_dwordx4 v[138:141], v[2:3], off
	v_or_b32_e32 v0, s1, v214
	v_min_u32_e32 v0, 0x7ff, v0
	v_mul_u32_u24_e32 v0, 0x1200, v0
	v_lshlrev_b32_e32 v64, 1, v0
	v_lshl_add_u64 v[0:1], s[8:9], 0, v[64:65]
	v_lshl_add_u64 v[0:1], v[0:1], 0, v[194:195]
	global_load_dwordx4 v[114:117], v[0:1], off offset:3168
	global_load_dwordx4 v[118:121], v[0:1], off offset:3136
	global_load_dwordx4 v[122:125], v[0:1], off offset:3104
	global_load_dwordx4 v[126:129], v[0:1], off offset:3072
	v_readlane_b32 s1, v254, 61
	s_add_i32 s1, s1, s0
	v_mov_b32_e32 v1, s12
	v_add_u32_e32 v5, s1, v213
	v_readlane_b32 s1, v254, 62
	v_sub_u32_e32 v5, v5, v214
	s_add_i32 s1, s1, s34
	v_lshl_add_u64 v[200:201], s[4:5], 0, v[196:197]
	v_mad_u32_u24 v197, v216, s58, v1
	v_subrev_u32_e32 v222, s34, v5
	v_add_u32_e32 v5, s1, v214
	v_mul_u32_u24_e32 v0, 0x90, v216
	v_add_u32_e32 v1, 0x480, v197
	v_add_u32_e32 v2, 0x900, v197
	v_add_u32_e32 v3, 0xd80, v197
	v_add_u32_e32 v4, s12, v196
	v_subrev_u32_e32 v5, s0, v5
	v_mov_b32_e32 v64, v65
	v_sub_u32_e32 v227, v5, v213
	v_mov_b32_e32 v66, v65
	v_mov_b32_e32 v67, v65
	v_mov_b32_e32 v68, v65
	v_mov_b32_e32 v69, v65
	v_mov_b32_e32 v70, v65
	v_mov_b32_e32 v71, v65
	v_mov_b32_e32 v72, v65
	v_mov_b32_e32 v73, v65
	v_mov_b32_e32 v74, v65
	v_mov_b32_e32 v75, v65
	v_mov_b32_e32 v76, v65
	v_mov_b32_e32 v77, v65
	v_mov_b32_e32 v78, v65
	v_mov_b32_e32 v79, v65
	v_mov_b32_e32 v186, 0
	v_add_u32_e32 v223, v4, v0
	v_add_u32_e32 v224, v1, v196
	v_add_u32_e32 v225, v2, v196
	v_add_u32_e32 v226, v3, v196
	v_mov_b64_e32 v[0:1], v[64:65]
	v_mov_b64_e32 v[32:33], v[64:65]
	v_lshl_add_u64 v[198:199], s[8:9], 0, v[194:195]
	v_add_u32_e32 v220, s0, v216
	v_add_u32_e32 v221, s0, v214
	s_mov_b32 s8, 0
	s_mov_b32 s9, 2
	v_mov_b32_e32 v195, 0
	v_mov_b64_e32 v[2:3], v[66:67]
	v_mov_b64_e32 v[4:5], v[68:69]
	v_mov_b64_e32 v[6:7], v[70:71]
	v_mov_b64_e32 v[8:9], v[72:73]
	v_mov_b64_e32 v[10:11], v[74:75]
	v_mov_b64_e32 v[12:13], v[76:77]
	v_mov_b64_e32 v[14:15], v[78:79]
	v_mov_b64_e32 v[34:35], v[66:67]
	v_mov_b64_e32 v[36:37], v[68:69]
	v_mov_b64_e32 v[38:39], v[70:71]
	v_mov_b64_e32 v[40:41], v[72:73]
	v_mov_b64_e32 v[42:43], v[74:75]
	v_mov_b64_e32 v[44:45], v[76:77]
	v_mov_b64_e32 v[46:47], v[78:79]
	v_mov_b32_e32 v16, 0
	v_mov_b32_e32 v17, v186
	v_mov_b32_e32 v18, v186
	v_mov_b32_e32 v19, v186
	v_mov_b32_e32 v20, v186
	v_mov_b32_e32 v21, v186
	v_mov_b32_e32 v22, v186
	v_mov_b32_e32 v23, v186
	v_mov_b32_e32 v24, v186
	v_mov_b32_e32 v25, v186
	v_mov_b32_e32 v26, v186
	v_mov_b32_e32 v27, v186
	v_mov_b32_e32 v28, v186
	v_mov_b32_e32 v29, v186
	v_mov_b32_e32 v30, v186
	v_mov_b32_e32 v31, v186
.LBB0_396:
	s_add_i32 s4, s9, -1
	s_cmp_lt_i32 s4, s7
	s_cselect_b64 s[0:1], -1, 0
	s_cmp_ge_i32 s4, s7
	s_cbranch_scc1 .LBB0_398
	s_nop 0
	v_add_u32_e32 v48, s8, v221
	v_add_u32_e32 v48, 0xffffffa0, v48
	v_med3_i32 v48, v48, 0, v243
	v_mul_u32_u24_e32 v64, 0x1200, v48
	v_lshl_add_u64 v[48:49], v[64:65], 1, v[198:199]
	v_add_u32_e32 v52, s8, v220
	global_load_dwordx4 v[146:149], v[48:49], off offset:3072
	global_load_dwordx4 v[150:153], v[48:49], off offset:3104
	global_load_dwordx4 v[154:157], v[48:49], off offset:3136
	global_load_dwordx4 v[158:161], v[48:49], off offset:3168
	v_add_u32_e32 v48, 0xffffffa0, v52
	v_med3_i32 v48, v48, 0, v243
	v_add_u32_e32 v50, 0xffffffa8, v52
	v_mul_u32_u24_e32 v64, 0x1200, v48
	v_med3_i32 v50, v50, 0, v243
	v_lshl_add_u64 v[48:49], v[64:65], 1, v[200:201]
	v_mul_u32_u24_e32 v64, 0x1200, v50
	v_lshl_add_u64 v[50:51], v[64:65], 1, v[200:201]
	global_load_dwordx4 v[162:165], v[48:49], off
	global_load_dwordx4 v[166:169], v[50:51], off
	v_add_u32_e32 v48, 0xffffffb0, v52
	v_med3_i32 v48, v48, 0, v243
	v_add_u32_e32 v50, 0xffffffb8, v52
	v_mul_u32_u24_e32 v64, 0x1200, v48
	v_med3_i32 v50, v50, 0, v243
	v_lshl_add_u64 v[48:49], v[64:65], 1, v[200:201]
	v_mul_u32_u24_e32 v64, 0x1200, v50
	v_lshl_add_u64 v[50:51], v[64:65], 1, v[200:201]
	global_load_dwordx4 v[170:173], v[48:49], off
	global_load_dwordx4 v[174:177], v[50:51], off
	s_waitcnt vmcnt(8) lgkmcnt(0)
	s_branch .Lgo_398

; __device__ __forceinline__ float xor32_max(float v) { auto rr = __builtin_amdgcn_permlane32_swap(__float_as_uint(v), __float_as_uint(v), false, false); return fmaxf(__uint_as_float(rr[0]), __uint_as_float(rr[1])); }
; __device__ __forceinline__ int crow(int r, int h) { return (r & 3) + 8 * (r >> 2) + 4 * h; }
; template <int MODE>
; __device__ __forceinline__ void soft_compute(SoftState& st, const bf16x8 (&qf)[4], const KV& t, int k0, int kst, int qp, int W, int dilm1, bool lane_ok, bool diag, const WaveCtx& c) {
;     store_v(t.vr, c);
;     VF vf; read_vf(vf, c);
;     f32x16 s = qk_ref(t.kf, qf, st.negm);
;     if (MODE == 0) {
;         const int relb = qp - k0;
;         const bool cls_ok = ((relb & dilm1) == 0);
; #pragma unroll
;         for (int r = 0; r < 16; ++r) {
;             const unsigned rel = (unsigned)(relb - kst * crow(r, c.h));
;             s[r] = (cls_ok && rel <= (unsigned)W) ? s[r] : -1e30f;
;         }
;     } else if (diag) {
; #pragma unroll
;         for (int r = 0; r < 16; ++r) { const int kp = k0 + crow(r, c.h); s[r] = (kp <= qp) ? s[r] : -1e30f; }
;     } else if (__ballot(!lane_ok) != 0ull) {
; #pragma unroll
;         for (int r = 0; r < 16; ++r) s[r] = lane_ok ? s[r] : -1e30f;
;     }
;     float mx = fmaxf(fmaxf(s[0], s[1]), fmaxf(s[2], s[3]));
; #pragma unroll
;     for (int r = 4; r < 16; r += 4) mx = fmaxf(mx, fmaxf(fmaxf(s[r], s[r + 1]), fmaxf(s[r + 2], s[r + 3])));
;     mx = xor32_max(mx);
;     if (__ballot(mx > 8.0f) != 0ull) {
;         const float d = fmaxf(mx, 0.f), scl = __builtin_amdgcn_exp2f(-d);
;         st.l *= scl; st.m += d;
;         const float nm = -st.m;
; #pragma unroll
;         for (int r = 0; r < 16; ++r) { st.o[0][r] *= scl; st.o[1][r] *= scl; s[r] -= d; st.negm[r] = nm; }
.Lgo_398:
	v_mfma_f32_32x32x16_bf16 v[48:63], v[126:129], v[98:101], v[16:31]
	v_add_u32_e32 v64, v197, v196
	v_add_u32_e32 v229, s8, v222
	ds_write_b128 v224, v[142:145]
	ds_write_b128 v225, v[130:133]
	ds_write_b128 v226, v[134:137]
	ds_write_b128 v64, v[138:141]
	v_add_u32_e32 v64, 0xffffff80, v229
	v_cmp_lt_u32_e32 vcc, s69, v64
	v_add_u32_e32 v76, 0xffffff7c, v227
	v_mfma_f32_32x32x16_bf16 v[48:63], v[122:125], v[102:105], v[48:63]
	v_add_u32_e32 v75, 0xffffff7d, v227
	v_add_u32_e32 v78, 0xffffff76, v227
	v_add_u32_e32 v77, 0xffffff77, v227
	v_add_u32_e32 v230, s12, v215
	ds_read_b64_tr_b16 v[70:71], v230
	ds_read_b64_tr_b16 v[72:73], v230 offset:1152
	ds_read_b64_tr_b16 v[68:69], v230 offset:1216
	ds_read_b64_tr_b16 v[66:67], v230 offset:64
	ds_read_b64_tr_b16 v[182:183], v230 offset:2304
	ds_read_b64_tr_b16 v[184:185], v230 offset:3456
	ds_read_b64_tr_b16 v[180:181], v230 offset:3520
	ds_read_b64_tr_b16 v[178:179], v230 offset:2368
	v_mfma_f32_32x32x16_bf16 v[48:63], v[118:121], v[106:109], v[48:63]
	v_mfma_f32_32x32x16_bf16 v[48:63], v[114:117], v[110:113], v[48:63]
	s_nop 11
	v_cndmask_b32_e32 v64, v244, v49, vcc
	v_cmp_gt_u32_e32 vcc, s13, v227
	v_add_u32_e32 v49, 0xffffff74, v227
	s_nop 0
	v_cndmask_b32_e32 v74, v244, v48, vcc
	v_cmp_lt_u32_e32 vcc, s69, v76
	v_add_u32_e32 v48, 0xffffff75, v227
	s_nop 0
	v_cndmask_b32_e32 v51, v244, v51, vcc
	v_cmp_lt_u32_e32 vcc, s69, v75
	s_nop 1
	v_cndmask_b32_e32 v75, v244, v50, vcc
	v_cmp_lt_u32_e32 vcc, s69, v78
	v_add_u32_e32 v50, 0xffffff65, v227
	s_nop 0
	v_cndmask_b32_e32 v53, v244, v53, vcc
	v_cmp_lt_u32_e32 vcc, s69, v77
	s_nop 1
	v_cndmask_b32_e32 v76, v244, v52, vcc
	v_cmp_lt_u32_e32 vcc, s69, v49
	v_add_u32_e32 v49, 0xffffff6e, v227
	s_nop 0
	v_cndmask_b32_e32 v52, v244, v55, vcc
	v_cmp_lt_u32_e32 vcc, s69, v48
	v_add_u32_e32 v48, 0xffffff6f, v227
	s_nop 0
	v_cndmask_b32_e32 v77, v244, v54, vcc
	v_cmp_lt_u32_e32 vcc, s69, v49
	v_add_u32_e32 v49, 0xffffff6c, v227
	s_nop 0
	v_cndmask_b32_e32 v55, v244, v57, vcc
	v_cmp_lt_u32_e32 vcc, s69, v48
	v_add_u32_e32 v48, 0xffffff6d, v227
	s_nop 0
	v_cndmask_b32_e32 v56, v244, v56, vcc
	v_cmp_lt_u32_e32 vcc, s69, v49
	v_add_u32_e32 v49, 0xffffff67, v227
	s_nop 0
	v_cndmask_b32_e32 v54, v244, v59, vcc
	v_cmp_lt_u32_e32 vcc, s69, v48
	v_add_u32_e32 v48, 0xffffff66, v227
	v_max_f32_e32 v59, v64, v64
	v_cndmask_b32_e32 v58, v244, v58, vcc
	v_cmp_lt_u32_e32 vcc, s69, v48
	s_nop 1
	v_cndmask_b32_e32 v48, v244, v61, vcc
	v_cmp_lt_u32_e32 vcc, s69, v49
	v_add_u32_e32 v49, 0xffffff64, v227
	v_max_f32_e32 v61, v75, v75
	v_cndmask_b32_e32 v57, v244, v60, vcc
	v_cmp_lt_u32_e32 vcc, s69, v49
	v_max_f32_e32 v60, v74, v74
	v_max_f32_e32 v59, v60, v59
	v_cndmask_b32_e32 v49, v244, v63, vcc
	v_cmp_lt_u32_e32 vcc, s69, v50
	v_max_f32_e32 v60, v51, v51
	v_max_f32_e32 v60, v61, v60
	v_cndmask_b32_e32 v50, v244, v62, vcc
	v_max_f32_e32 v61, v52, v52
	v_max_f32_e32 v62, v77, v77
	v_max_f32_e32 v61, v62, v61
	v_max3_f32 v61, v76, v53, v61
	v_max3_f32 v59, v59, v60, v61
	v_max_f32_e32 v60, v54, v54
	v_max_f32_e32 v61, v58, v58
	v_max_f32_e32 v60, v61, v60
	v_max_f32_e32 v61, v49, v49
	v_max_f32_e32 v62, v50, v50
	v_max_f32_e32 v61, v62, v61
	v_max3_f32 v60, v56, v55, v60
	v_max3_f32 v61, v57, v48, v61
	v_max3_f32 v59, v59, v60, v61
	v_mov_b32_e32 v60, v59
	s_nop 1
	v_permlane32_swap_b32_e32 v59, v60
	v_max_f32_e32 v60, v60, v60
	v_max_f32_e32 v59, v59, v59
	v_max_f32_e32 v59, v59, v60
	v_cmp_lt_f32_e32 vcc, s70, v59
	s_cbranch_vccz .LBB0_400
	v_max_f32_e32 v16, v59, v59
	v_max_f32_e32 v17, 0, v16
	v_exp_f32_e64 v16, -v17
	v_add_f32_e32 v195, v195, v17
	v_xor_b32_e32 v82, 0x80000000, v195
	v_sub_f32_e32 v74, v74, v17
	v_mul_f32_e32 v186, v186, v16
	v_pk_mul_f32 v[14:15], v[14:15], v[16:17] op_sel_hi:[1,0]
	v_pk_mul_f32 v[12:13], v[12:13], v[16:17] op_sel_hi:[1,0]
	v_pk_mul_f32 v[10:11], v[10:11], v[16:17] op_sel_hi:[1,0]
	v_pk_mul_f32 v[8:9], v[8:9], v[16:17] op_sel_hi:[1,0]
	v_pk_mul_f32 v[6:7], v[6:7], v[16:17] op_sel_hi:[1,0]
	v_pk_mul_f32 v[4:5], v[4:5], v[16:17] op_sel_hi:[1,0]
	v_pk_mul_f32 v[2:3], v[2:3], v[16:17] op_sel_hi:[1,0]
	v_pk_mul_f32 v[0:1], v[0:1], v[16:17] op_sel_hi:[1,0]
	v_pk_mul_f32 v[46:47], v[46:47], v[16:17] op_sel_hi:[1,0]
	v_pk_mul_f32 v[44:45], v[44:45], v[16:17] op_sel_hi:[1,0]
	v_pk_mul_f32 v[42:43], v[42:43], v[16:17] op_sel_hi:[1,0]
	v_pk_mul_f32 v[40:41], v[40:41], v[16:17] op_sel_hi:[1,0]
	v_pk_mul_f32 v[38:39], v[38:39], v[16:17] op_sel_hi:[1,0]
	v_pk_mul_f32 v[36:37], v[36:37], v[16:17] op_sel_hi:[1,0]
	v_pk_mul_f32 v[34:35], v[34:35], v[16:17] op_sel_hi:[1,0]
	v_pk_mul_f32 v[32:33], v[32:33], v[16:17] op_sel_hi:[1,0]
	v_sub_f32_e32 v64, v64, v17
	v_sub_f32_e32 v75, v75, v17
	v_sub_f32_e32 v51, v51, v17
	v_sub_f32_e32 v76, v76, v17
	v_sub_f32_e32 v53, v53, v17
	v_sub_f32_e32 v77, v77, v17
	v_sub_f32_e32 v52, v52, v17
	v_sub_f32_e32 v56, v56, v17
	v_sub_f32_e32 v55, v55, v17
	v_sub_f32_e32 v58, v58, v17
	v_sub_f32_e32 v54, v54, v17
	v_sub_f32_e32 v57, v57, v17
	v_sub_f32_e32 v48, v48, v17
	v_sub_f32_e32 v50, v50, v17
	v_sub_f32_e32 v49, v49, v17
	v_mov_b32_e32 v83, v82
	v_mov_b32_e32 v84, v82
	v_mov_b32_e32 v85, v82
	v_mov_b32_e32 v86, v82
	v_mov_b32_e32 v87, v82
	v_mov_b32_e32 v88, v82
	v_mov_b32_e32 v89, v82
	v_mov_b32_e32 v90, v82
	v_mov_b32_e32 v91, v82
	v_mov_b32_e32 v92, v82
	v_mov_b32_e32 v93, v82
	v_mov_b32_e32 v94, v82
	v_mov_b32_e32 v95, v82
	v_mov_b32_e32 v96, v82
	v_mov_b32_e32 v97, v82
	v_mov_b32_e32 v16, v82
	v_mov_b32_e32 v17, v82
	v_mov_b32_e32 v18, v82
	v_mov_b32_e32 v19, v82
	v_mov_b32_e32 v20, v82
	v_mov_b32_e32 v21, v82
	v_mov_b32_e32 v22, v82
	v_mov_b32_e32 v23, v82
	v_mov_b32_e32 v24, v82
	v_mov_b32_e32 v25, v82
	v_mov_b32_e32 v26, v82
	v_mov_b32_e32 v27, v82
	v_mov_b32_e32 v28, v82
	v_mov_b32_e32 v29, v82
	v_mov_b32_e32 v30, v82
	v_mov_b32_e32 v31, v82
	s_branch .LBB0_401

; __device__ __forceinline__ float xor32_sum(float v) { auto rr = __builtin_amdgcn_permlane32_swap(__float_as_uint(v), __float_as_uint(v), false, false); return __uint_as_float(rr[0]) + __uint_as_float(rr[1]); }
; template <int MODE>
; __device__ __forceinline__ void soft_compute(SoftState& st, const bf16x8 (&qf)[4], const KV& t, int k0, int kst, int qp, int W, int dilm1, bool lane_ok, bool diag, const WaveCtx& c) {
;     ...
;     float ps = 0.f;
; #pragma unroll
;     for (int r = 0; r < 16; ++r) { const float p = __builtin_amdgcn_exp2f(s[r]); s[r] = p; ps += p; }
;     st.l += xor32_sum(ps);
;     pv(st.o, s, vf);
; __device__ __forceinline__ void unit_A2(const bf16_t* qkv, bf16_t* outA, int b, int slot, int blk, int w, LAS unsigned char* lds, const WaveCtx& c) {
;     ...
;         for (int i = 0; i < ntot; i += 2) {
;             if (i + 1 < ntot) issue_kv<true>(tb, kbase, vbase, ks0 + 32 * (i + 1), 1, c);
;             soft_compute<0>(st, qf, ta, ks0 + 32 * i, 1, qp1, 128, 0, true, false, c);
;             if (i + 1 >= ntot) break;
;             if (i + 2 < ntot) issue_kv<true>(ta, kbase, vbase, ks0 + 32 * (i + 2), 1, c);
.LBB0_401:
	v_exp_f32_e32 v59, v74
	v_exp_f32_e32 v60, v64
	v_exp_f32_e32 v61, v75
	v_exp_f32_e32 v51, v51
	v_add_f32_e32 v62, 0, v59
	v_exp_f32_e32 v63, v76
	v_add_f32_e32 v62, v60, v62
	v_exp_f32_e32 v64, v53
	v_add_f32_e32 v62, v61, v62
	v_exp_f32_e32 v74, v77
	v_add_f32_e32 v53, v51, v62
	v_exp_f32_e32 v62, v52
	v_add_f32_e32 v53, v63, v53
	v_exp_f32_e32 v56, v56
	v_add_f32_e32 v53, v64, v53
	v_exp_f32_e32 v75, v55
	v_add_f32_e32 v53, v74, v53
	v_exp_f32_e32 v58, v58
	v_add_f32_e32 v52, v62, v53
	v_add_f32_e32 v52, v56, v52
	v_add_f32_e32 v52, v75, v52
	v_exp_f32_e32 v77, v54
	v_add_f32_e32 v76, v58, v52
	v_exp_f32_e32 v57, v57
	v_cvt_pk_bf16_f32 v52, v59, v60
	v_cvt_pk_bf16_f32 v53, v61, v51
	v_cvt_pk_bf16_f32 v54, v63, v64
	v_cvt_pk_bf16_f32 v55, v74, v62
	v_exp_f32_e32 v48, v48
	v_exp_f32_e32 v50, v50
	s_waitcnt lgkmcnt(6)
	v_mfma_f32_32x32x16_bf16 v[0:15], v[70:73], v[52:55], v[0:15]
	v_add_f32_e32 v51, v77, v76
	v_exp_f32_e32 v49, v49
	v_add_f32_e32 v51, v57, v51
	v_add_f32_e32 v51, v48, v51
	v_add_f32_e32 v51, v50, v51
	v_add_f32_e32 v51, v49, v51
	v_cvt_pk_bf16_f32 v188, v56, v75
	s_waitcnt lgkmcnt(4)
	v_mfma_f32_32x32x16_bf16 v[32:47], v[66:69], v[52:55], v[32:47]
	v_mov_b32_e32 v52, v51
	v_cvt_pk_bf16_f32 v189, v58, v77
	s_nop 0
	v_mov_b64_e32 v[80:81], v[14:15]
	v_permlane32_swap_b32_e32 v51, v52
	v_cvt_pk_bf16_f32 v190, v57, v48
	v_cvt_pk_bf16_f32 v191, v50, v49
	v_mov_b64_e32 v[78:79], v[12:13]
	v_mov_b64_e32 v[76:77], v[10:11]
	v_mov_b64_e32 v[74:75], v[8:9]
	v_mov_b64_e32 v[72:73], v[6:7]
	v_mov_b64_e32 v[70:71], v[4:5]
	v_mov_b64_e32 v[68:69], v[2:3]
	v_mov_b64_e32 v[66:67], v[0:1]
	v_add_f32_e32 v0, v51, v52
	v_mov_b64_e32 v[62:63], v[46:47]
	v_mov_b64_e32 v[60:61], v[44:45]
	v_mov_b64_e32 v[58:59], v[42:43]
	v_mov_b64_e32 v[56:57], v[40:41]
	v_mov_b64_e32 v[54:55], v[38:39]
	v_mov_b64_e32 v[52:53], v[36:37]
	v_mov_b64_e32 v[50:51], v[34:35]
	v_mov_b64_e32 v[48:49], v[32:33]
	s_waitcnt lgkmcnt(2)
	v_mfma_f32_32x32x16_bf16 v[66:81], v[182:185], v[188:191], v[66:81]
	v_add_f32_e32 v228, v186, v0
	s_andn2_b64 vcc, exec, s[0:1]
	s_waitcnt lgkmcnt(0)
	v_mfma_f32_32x32x16_bf16 v[48:63], v[178:181], v[188:191], v[48:63]
	s_cbranch_vccnz .LBB0_406
	s_cmp_ge_i32 s9, s7
	s_cselect_b64 s[0:1], -1, 0
	s_and_b64 vcc, exec, s[0:1]
	s_cbranch_vccnz .LBB0_404
	v_add_u32_e32 v0, s8, v221
	v_subrev_u32_e32 v0, 64, v0
	v_med3_i32 v0, v0, 0, v243
	v_mul_u32_u24_e32 v64, 0x1200, v0
	v_lshl_add_u64 v[0:1], v[64:65], 1, v[198:199]
	v_add_u32_e32 v4, s8, v220
	global_load_dwordx4 v[126:129], v[0:1], off offset:3072
	global_load_dwordx4 v[122:125], v[0:1], off offset:3104
	global_load_dwordx4 v[118:121], v[0:1], off offset:3136
	global_load_dwordx4 v[114:117], v[0:1], off offset:3168
	v_subrev_u32_e32 v0, 64, v4
	v_med3_i32 v0, v0, 0, v243
	v_subrev_u32_e32 v2, 56, v4
	v_mul_u32_u24_e32 v64, 0x1200, v0
	v_med3_i32 v2, v2, 0, v243
	v_lshl_add_u64 v[0:1], v[64:65], 1, v[200:201]
	v_mul_u32_u24_e32 v64, 0x1200, v2
	v_lshl_add_u64 v[2:3], v[64:65], 1, v[200:201]
	global_load_dwordx4 v[138:141], v[0:1], off
	global_load_dwordx4 v[142:145], v[2:3], off
	v_subrev_u32_e32 v0, 48, v4
	v_med3_i32 v0, v0, 0, v243
	v_subrev_u32_e32 v2, 40, v4
	v_mul_u32_u24_e32 v64, 0x1200, v0
	v_med3_i32 v2, v2, 0, v243
	v_lshl_add_u64 v[0:1], v[64:65], 1, v[200:201]
	v_mul_u32_u24_e32 v64, 0x1200, v2
	v_lshl_add_u64 v[2:3], v[64:65], 1, v[200:201]
	global_load_dwordx4 v[130:133], v[0:1], off
	global_load_dwordx4 v[134:137], v[2:3], off
	s_waitcnt vmcnt(8)
	s_branch .Lgo_404
.LBB0_404:
	s_waitcnt vmcnt(0)
; __device__ __forceinline__ float xor32_max(float v) { auto rr = __builtin_amdgcn_permlane32_swap(__float_as_uint(v), __float_as_uint(v), false, false); return fmaxf(__uint_as_float(rr[0]), __uint_as_float(rr[1])); }
; __device__ __forceinline__ int crow(int r, int h) { return (r & 3) + 8 * (r >> 2) + 4 * h; }
; template <int MODE>
; __device__ __forceinline__ void soft_compute(SoftState& st, const bf16x8 (&qf)[4], const KV& t, int k0, int kst, int qp, int W, int dilm1, bool lane_ok, bool diag, const WaveCtx& c) {
;     store_v(t.vr, c);
;     VF vf; read_vf(vf, c);
;     f32x16 s = qk_ref(t.kf, qf, st.negm);
;     if (MODE == 0) {
;         const int relb = qp - k0;
;         const bool cls_ok = ((relb & dilm1) == 0);
; #pragma unroll
;         for (int r = 0; r < 16; ++r) {
;             const unsigned rel = (unsigned)(relb - kst * crow(r, c.h));
;             s[r] = (cls_ok && rel <= (unsigned)W) ? s[r] : -1e30f;
;         }
;     } else if (diag) {
; #pragma unroll
;         for (int r = 0; r < 16; ++r) { const int kp = k0 + crow(r, c.h); s[r] = (kp <= qp) ? s[r] : -1e30f; }
;     } else if (__ballot(!lane_ok) != 0ull) {
; #pragma unroll
;         for (int r = 0; r < 16; ++r) s[r] = lane_ok ? s[r] : -1e30f;
;     }
;     float mx = fmaxf(fmaxf(s[0], s[1]), fmaxf(s[2], s[3]));
; #pragma unroll
;     for (int r = 4; r < 16; r += 4) mx = fmaxf(mx, fmaxf(fmaxf(s[r], s[r + 1]), fmaxf(s[r + 2], s[r + 3])));
;     mx = xor32_max(mx);
;     if (__ballot(mx > 8.0f) != 0ull) {
;         const float d = fmaxf(mx, 0.f), scl = __builtin_amdgcn_exp2f(-d);
;         st.l *= scl; st.m += d;
;         const float nm = -st.m;
; #pragma unroll
;         for (int r = 0; r < 16; ++r) { st.o[0][r] *= scl; st.o[1][r] *= scl; s[r] -= d; st.negm[r] = nm; }
.Lgo_404:
	v_mfma_f32_32x32x16_bf16 v[82:97], v[146:149], v[98:101], v[82:97]
	v_add_u32_e32 v1, 0xffffffa0, v229
	v_subrev_u32_e32 v0, 32, v227
	v_cmp_lt_u32_e32 vcc, s69, v1
	v_add_u32_e32 v1, 0xffffff5c, v227
	ds_write_b128 v223, v[162:165]
	ds_write_b128 v224, v[166:169]
	ds_write_b128 v225, v[170:173]
	ds_write_b128 v226, v[174:177]
	ds_read_b64_tr_b16 v[190:191], v230
	ds_read_b64_tr_b16 v[192:193], v230 offset:1152
	ds_read_b64_tr_b16 v[182:183], v230 offset:2304
	ds_read_b64_tr_b16 v[184:185], v230 offset:3456
	ds_read_b64_tr_b16 v[186:187], v230 offset:64
	ds_read_b64_tr_b16 v[188:189], v230 offset:1216
	ds_read_b64_tr_b16 v[178:179], v230 offset:2368
	ds_read_b64_tr_b16 v[180:181], v230 offset:3520
	v_mfma_f32_32x32x16_bf16 v[82:97], v[150:153], v[102:105], v[82:97]
	v_mfma_f32_32x32x16_bf16 v[82:97], v[154:157], v[106:109], v[82:97]
	v_mfma_f32_32x32x16_bf16 v[82:97], v[158:161], v[110:113], v[82:97]
	s_nop 11
	v_cndmask_b32_e32 v83, v244, v83, vcc
	v_cmp_gt_u32_e32 vcc, s13, v0
	v_add_u32_e32 v0, 0xffffff5d, v227
	s_nop 0
	v_cndmask_b32_e32 v82, v244, v82, vcc
	v_cmp_lt_u32_e32 vcc, s69, v1
	v_add_u32_e32 v1, 0xffffff56, v227
	s_nop 0
	v_cndmask_b32_e32 v85, v244, v85, vcc
	v_cmp_lt_u32_e32 vcc, s69, v0
	v_add_u32_e32 v0, 0xffffff57, v227
	s_nop 0
	v_cndmask_b32_e32 v84, v244, v84, vcc
	v_cmp_lt_u32_e32 vcc, s69, v1
	v_add_u32_e32 v1, 0xffffff54, v227
	v_max_f32_e32 v2, v84, v84
	v_cndmask_b32_e32 v229, v244, v87, vcc
	v_cmp_lt_u32_e32 vcc, s69, v0
	v_add_u32_e32 v0, 0xffffff55, v227
	s_nop 0
	v_cndmask_b32_e32 v248, v244, v86, vcc
	v_cmp_lt_u32_e32 vcc, s69, v1
	v_add_u32_e32 v1, 0xffffff4e, v227
	s_nop 0
	v_cndmask_b32_e32 v231, v244, v89, vcc
	v_cmp_lt_u32_e32 vcc, s69, v0
	v_add_u32_e32 v0, 0xffffff4f, v227
	s_nop 0
	v_cndmask_b32_e32 v247, v244, v88, vcc
	v_cmp_lt_u32_e32 vcc, s69, v1
	v_add_u32_e32 v1, 0xffffff4c, v227
	v_max_f32_e32 v3, v247, v247
	v_cndmask_b32_e32 v230, v244, v91, vcc
	v_cmp_lt_u32_e32 vcc, s69, v0
	v_add_u32_e32 v0, 0xffffff4d, v227
	s_nop 0
	v_cndmask_b32_e32 v249, v244, v90, vcc
	v_cmp_lt_u32_e32 vcc, s69, v1
	v_add_u32_e32 v1, 0xffffff46, v227
	s_nop 0
	v_cndmask_b32_e32 v86, v244, v93, vcc
	v_cmp_lt_u32_e32 vcc, s69, v0
	v_add_u32_e32 v0, 0xffffff47, v227
	s_nop 0
	v_cndmask_b32_e32 v92, v244, v92, vcc
	v_cmp_lt_u32_e32 vcc, s69, v1
	v_add_u32_e32 v1, 0xffffff44, v227
	s_nop 0
	v_cndmask_b32_e32 v88, v244, v95, vcc
	v_cmp_lt_u32_e32 vcc, s69, v0
	v_add_u32_e32 v0, 0xffffff45, v227
	s_nop 0
	v_cndmask_b32_e32 v90, v244, v94, vcc
	v_cmp_lt_u32_e32 vcc, s69, v1
	v_max_f32_e32 v1, v82, v82
	s_nop 0
	v_cndmask_b32_e32 v87, v244, v97, vcc
	v_cmp_lt_u32_e32 vcc, s69, v0
	v_max_f32_e32 v0, v83, v83
	v_max_f32_e32 v0, v1, v0
	v_max_f32_e32 v1, v85, v85
	v_max_f32_e32 v1, v2, v1
	v_max_f32_e32 v2, v231, v231
	v_max_f32_e32 v2, v3, v2
	v_max3_f32 v2, v248, v229, v2
	v_cndmask_b32_e32 v89, v244, v96, vcc
	v_max3_f32 v0, v0, v1, v2
	v_max_f32_e32 v1, v86, v86
	v_max_f32_e32 v2, v92, v92
	v_max_f32_e32 v1, v2, v1
	v_max_f32_e32 v2, v87, v87
	v_max_f32_e32 v3, v89, v89
	v_max_f32_e32 v2, v3, v2
	v_max3_f32 v1, v249, v230, v1
	v_max3_f32 v2, v90, v88, v2
	v_max3_f32 v0, v0, v1, v2
	v_mov_b32_e32 v1, v0
	s_nop 1
	v_permlane32_swap_b32_e32 v0, v1
	v_max_f32_e32 v1, v1, v1
	v_max_f32_e32 v0, v0, v0
	v_max_f32_e32 v0, v0, v1
	v_cmp_lt_f32_e32 vcc, s70, v0
	s_cbranch_vccz .LBB0_407
	v_max_f32_e32 v0, v0, v0
	v_max_f32_e32 v17, 0, v0
	v_exp_f32_e64 v18, -v17
	v_add_f32_e32 v64, v195, v17
	v_xor_b32_e32 v16, 0x80000000, v64
	v_sub_f32_e32 v82, v82, v17
	v_mul_f32_e32 v91, v228, v18
	v_pk_mul_f32 v[14:15], v[80:81], v[18:19] op_sel_hi:[1,0]
	v_pk_mul_f32 v[12:13], v[78:79], v[18:19] op_sel_hi:[1,0]
	v_pk_mul_f32 v[10:11], v[76:77], v[18:19] op_sel_hi:[1,0]
	v_pk_mul_f32 v[8:9], v[74:75], v[18:19] op_sel_hi:[1,0]
	v_pk_mul_f32 v[6:7], v[72:73], v[18:19] op_sel_hi:[1,0]
	v_pk_mul_f32 v[4:5], v[70:71], v[18:19] op_sel_hi:[1,0]
	v_pk_mul_f32 v[2:3], v[68:69], v[18:19] op_sel_hi:[1,0]
	v_pk_mul_f32 v[0:1], v[66:67], v[18:19] op_sel_hi:[1,0]
	v_pk_mul_f32 v[46:47], v[62:63], v[18:19] op_sel_hi:[1,0]
	v_pk_mul_f32 v[44:45], v[60:61], v[18:19] op_sel_hi:[1,0]
	v_pk_mul_f32 v[42:43], v[58:59], v[18:19] op_sel_hi:[1,0]
	v_pk_mul_f32 v[40:41], v[56:57], v[18:19] op_sel_hi:[1,0]
	v_pk_mul_f32 v[38:39], v[54:55], v[18:19] op_sel_hi:[1,0]
	v_pk_mul_f32 v[36:37], v[52:53], v[18:19] op_sel_hi:[1,0]
	v_pk_mul_f32 v[34:35], v[50:51], v[18:19] op_sel_hi:[1,0]
	v_pk_mul_f32 v[32:33], v[48:49], v[18:19] op_sel_hi:[1,0]
	v_sub_f32_e32 v83, v83, v17
	v_sub_f32_e32 v84, v84, v17
	v_sub_f32_e32 v85, v85, v17
	v_sub_f32_e32 v248, v248, v17
	v_sub_f32_e32 v229, v229, v17
	v_sub_f32_e32 v247, v247, v17
	v_sub_f32_e32 v231, v231, v17
	v_sub_f32_e32 v249, v249, v17
	v_sub_f32_e32 v230, v230, v17
	v_sub_f32_e32 v92, v92, v17
	v_sub_f32_e32 v86, v86, v17
	v_sub_f32_e32 v90, v90, v17
	v_sub_f32_e32 v88, v88, v17
	v_sub_f32_e32 v89, v89, v17
	v_sub_f32_e32 v87, v87, v17
	v_mov_b32_e32 v17, v16
	v_mov_b32_e32 v18, v16
	v_mov_b32_e32 v19, v16
	v_mov_b32_e32 v20, v16
	v_mov_b32_e32 v21, v16
	v_mov_b32_e32 v22, v16
	v_mov_b32_e32 v23, v16
	v_mov_b32_e32 v24, v16
	v_mov_b32_e32 v25, v16
	v_mov_b32_e32 v26, v16
	v_mov_b32_e32 v27, v16
	v_mov_b32_e32 v28, v16
	v_mov_b32_e32 v29, v16
	v_mov_b32_e32 v30, v16
	v_mov_b32_e32 v31, v16
	s_branch .LBB0_408

; __device__ __forceinline__ void unit_A2(const bf16_t* qkv, bf16_t* outA, int b, int slot, int blk, int w, LAS unsigned char* lds, const WaveCtx& c) {
;     ...
;     for (int g = 1; g < 3; ++g) {
;         const int dil = 1 << (2 * g), W = 128 * dil, head = 4 * g + slot;
;         bf16x8 qf[4]; load_q(qf, rowb + (size_t)qp * LDQ + head * 64, c.h);
;         const bf16_t* kbase = rowb + MIXW + head * 64; const bf16_t* vbase = rowb + 2 * MIXW + head * 64;
;         int ks0, ks1 = 0, n0, n1 = 0;
;         const int lo = 256 * blk - W;
;         if (g == 1) { ks0 = (lo < 0) ? (cls0 & 3) : (cls0 + lo); n0 = ((256 * blk + cls0 + 4 + 240 - ks0) / dil + 1 + 31) >> 5; }
;         else { const int c0 = cls0, c1 = cls0 + 4;
;             ks0 = (lo < 0) ? (c0 & (dil - 1)) : (c0 + lo); ks1 = (lo < 0) ? (c1 & (dil - 1)) : (c1 + lo);
;             n0 = ((256 * blk + c0 + 240 - ks0) / dil + 1 + 31) >> 5; n1 = ((256 * blk + c1 + 240 - ks1) / dil + 1 + 31) >> 5; }
.LBB0_420:
	s_lshl_b32 s25, s0, 1
	s_lshl_b32 s0, s0, 8
	v_readlane_b32 s6, v254, 27
	s_add_i32 s0, s0, s6
	s_ashr_i32 s1, s0, 31
	v_lshl_add_u64 v[48:49], s[0:1], 1, v[162:163]
	s_waitcnt vmcnt(0) lgkmcnt(0)
	global_load_dwordx4 v[98:101], v[48:49], off
	global_load_dwordx4 v[102:105], v[48:49], off offset:32
	global_load_dwordx4 v[106:109], v[48:49], off offset:64
	global_load_dwordx4 v[110:113], v[48:49], off offset:96
	s_lshl_b32 s23, 1, s25
	v_cvt_f32_u32_e32 v48, s23
	s_lshl_b32 s19, 0x80, s25
	s_sub_i32 s22, s78, s19
	v_readlane_b32 s7, v254, 28
	v_rcp_iflag_f32_e32 v48, v48
	s_cmp_lt_i32 s22, 0
	s_cselect_b64 s[6:7], -1, 0
	s_andn2_b64 vcc, exec, s[8:9]
	s_mov_b64 s[8:9], -1
	s_cbranch_vccz .LBB0_422
	s_add_i32 s21, s23, -1
	s_and_b32 s20, s21, s14
	s_add_i32 s24, s22, s14
	v_mul_f32_e32 v49, 0x4f7ffffe, v48
	s_and_b64 s[8:9], s[6:7], exec
	v_cvt_u32_f32_e32 v49, v49
	s_cselect_b32 s20, s20, s24
	s_and_b32 s21, s21, s15
	s_add_i32 s24, s22, s15
	s_and_b64 s[8:9], s[6:7], exec
	s_cselect_b32 s21, s21, s24
	s_sub_i32 s8, s17, s21
	s_sub_i32 s26, 0, s23
	v_readfirstlane_b32 s27, v49
	s_ashr_i32 s9, s8, 31
	s_mul_i32 s26, s26, s27
	s_add_i32 s8, s8, s9
	s_mul_hi_u32 s26, s27, s26
	s_xor_b32 s8, s8, s9
	s_add_i32 s27, s27, s26
	s_mul_hi_u32 s26, s8, s27
	s_mul_i32 s27, s26, s23
	s_sub_i32 s8, s8, s27
	s_sub_i32 s24, s16, s20
	s_sub_i32 s27, s8, s23
	s_add_i32 s28, s26, 1
	s_cmp_ge_u32 s8, s23
	s_cselect_b32 s26, s28, s26
	s_cselect_b32 s8, s27, s8
	s_add_i32 s27, s26, 1
	s_cmp_ge_u32 s8, s23
	s_cselect_b32 s8, s27, s26
	s_xor_b32 s8, s8, s9
	s_sub_i32 s8, s8, s9
	s_add_i32 s8, s8, 32
	s_ashr_i32 s26, s8, 5
	s_mov_b64 s[8:9], 0

; template <bool CLAMP>
; __device__ __forceinline__ void load_k(bf16x8 (&kf)[4], const bf16_t* kbase, int k0, int kst, const WaveCtx& c) {
;     int kp = k0 + kst * c.q; if (CLAMP) kp = kp < 0 ? 0 : (kp > SEQ - 1 ? SEQ - 1 : kp);
;     const bf16_t* kr = kbase + (size_t)kp * LDQ + 8 * c.h;
; #pragma unroll
;     for (int ks = 0; ks < 4; ++ks) kf[ks] = *(const bf16x8*)(kr + 16 * ks);
; }
; template <bool CLAMP>
; __device__ __forceinline__ void load_v(u32x4 (&vr)[4], const bf16_t* vbase, int k0, int kst, const WaveCtx& c) {
; #pragma unroll
;     for (int i = 0; i < 4; ++i) { const int p = c.lane + 64 * i, n = p >> 3; int kp = k0 + kst * n; if (CLAMP) kp = kp < 0 ? 0 : (kp > SEQ - 1 ? SEQ - 1 : kp);
;         vr[i] = *(const u32x4*)(vbase + (size_t)kp * LDQ + (p & 7) * 8); }
; __device__ __forceinline__ void unit_A2(const bf16_t* qkv, bf16_t* outA, int b, int slot, int blk, int w, LAS unsigned char* lds, const WaveCtx& c) {
;     ...
;         if (g == 1) { ks0 = (lo < 0) ? (cls0 & 3) : (cls0 + lo); n0 = ((256 * blk + cls0 + 4 + 240 - ks0) / dil + 1 + 31) >> 5; }
;         else { const int c0 = cls0, c1 = cls0 + 4;
;             ks0 = (lo < 0) ? (c0 & (dil - 1)) : (c0 + lo); ks1 = (lo < 0) ? (c1 & (dil - 1)) : (c1 + lo);
;             n0 = ((256 * blk + c0 + 240 - ks0) / dil + 1 + 31) >> 5; n1 = ((256 * blk + c1 + 240 - ks1) / dil + 1 + 31) >> 5; }
;         const int ntot = n0 + n1, step = 32 * dil;
;         KV ta, tb;
;         issue_kv<true>(ta, kbase, vbase, ks0, dil, c);
.LBB0_424:
	v_mul_f32_e32 v48, 0x4f7ffffe, v48
	v_cvt_u32_f32_e32 v48, v48
	s_sub_i32 s8, 0, s23
	s_ashr_i32 s6, s24, 31
	s_add_i32 s7, s24, s6
	v_readfirstlane_b32 s9, v48
	s_mul_i32 s8, s8, s9
	s_mul_hi_u32 s8, s9, s8
	s_xor_b32 s7, s7, s6
	s_add_i32 s9, s9, s8
	s_mul_hi_u32 s8, s7, s9
	s_mul_i32 s9, s8, s23
	s_sub_i32 s7, s7, s9
	s_sub_i32 s9, s7, s23
	s_add_i32 s22, s8, 1
	s_cmp_ge_u32 s7, s23
	s_cselect_b32 s8, s22, s8
	s_cselect_b32 s7, s9, s7
	s_add_i32 s9, s8, 1
	s_cmp_ge_u32 s7, s23
	s_cselect_b32 s7, s9, s8
	s_xor_b32 s7, s7, s6
	s_sub_i32 s6, s7, s6
	s_add_i32 s6, s6, 32
	s_ashr_i32 s8, s6, 5
	s_add_i32 s9, s8, s26
	s_cmp_lt_i32 s9, 1
	s_cbranch_scc1 .LBB0_437
	s_lshl_b64 s[0:1], s[0:1], 1
	s_add_u32 s6, s2, s0
	v_lshlrev_b32_e32 v198, s25, v173
	s_addc_u32 s7, s3, s1
	v_add_u32_e32 v48, s20, v198
	v_lshlrev_b32_e32 v199, s25, v174
	s_add_u32 s0, s10, s0
	v_med3_i32 v48, v48, 0, v243
	v_add_u32_e32 v50, s20, v199
	s_addc_u32 s1, s11, s1
	v_mul_u32_u24_e32 v64, 0x1200, v48
	v_med3_i32 v50, v50, 0, v243
	v_lshl_add_u64 v[48:49], v[64:65], 1, s[0:1]
	v_mov_b32_e32 v165, v65
	v_mul_u32_u24_e32 v64, 0x1200, v50
	v_lshl_add_u64 v[48:49], v[48:49], 0, v[164:165]
	v_lshl_add_u64 v[50:51], v[64:65], 1, s[0:1]
	v_lshlrev_b32_e32 v200, s25, v175
	v_lshl_add_u64 v[50:51], v[50:51], 0, v[164:165]
	global_load_dwordx4 v[114:117], v[48:49], off
	global_load_dwordx4 v[118:121], v[50:51], off
	v_add_u32_e32 v48, s20, v200
	v_lshlrev_b32_e32 v201, s25, v216
	v_med3_i32 v48, v48, 0, v243
	v_add_u32_e32 v50, s20, v201
	v_mul_u32_u24_e32 v64, 0x1200, v48
	v_med3_i32 v50, v50, 0, v243
	v_lshl_add_u64 v[48:49], v[64:65], 1, s[0:1]
	v_mul_u32_u24_e32 v64, 0x1200, v50
	v_lshl_add_u64 v[48:49], v[48:49], 0, v[164:165]
	v_lshl_add_u64 v[50:51], v[64:65], 1, s[0:1]
	v_lshlrev_b32_e32 v217, s25, v214
	v_lshl_add_u64 v[50:51], v[50:51], 0, v[164:165]
	global_load_dwordx4 v[130:133], v[48:49], off
	global_load_dwordx4 v[138:141], v[50:51], off
	v_add_u32_e32 v48, s20, v217
	v_med3_i32 v48, v48, 0, v243
	v_mul_u32_u24_e32 v64, 0x1200, v48
	v_lshl_add_u64 v[48:49], v[64:65], 1, s[6:7]
	v_mov_b32_e32 v195, v65
	v_lshl_add_u64 v[48:49], v[48:49], 0, v[194:195]
	global_load_dwordx4 v[122:125], v[48:49], off offset:3168
	global_load_dwordx4 v[126:129], v[48:49], off offset:3136
	global_load_dwordx4 v[134:137], v[48:49], off offset:3104
	global_load_dwordx4 v[142:145], v[48:49], off offset:3072
	s_mov_b32 s24, 0
	s_add_i32 s22, s25, 5
	s_add_i32 s23, s23, -1
	v_lshl_add_u64 v[166:167], s[6:7], 0, v[194:195]
	v_lshl_add_u64 v[168:169], s[0:1], 0, v[164:165]
	v_lshlrev_b32_e32 v165, s25, v213
	v_lshlrev_b32_e32 v195, s25, v177
	v_lshlrev_b32_e32 v218, s25, v178
	v_lshlrev_b32_e32 v219, s25, v179
	v_lshlrev_b32_e32 v220, s25, v180
	v_lshlrev_b32_e32 v221, s25, v181
	v_lshlrev_b32_e32 v222, s25, v182
	v_lshlrev_b32_e32 v223, s25, v183
	v_lshlrev_b32_e32 v224, s25, v184
	v_lshlrev_b32_e32 v225, s25, v185
	v_lshlrev_b32_e32 v226, s25, v186
	v_lshlrev_b32_e32 v227, s25, v187
	v_lshlrev_b32_e32 v228, s25, v188
	v_lshlrev_b32_e32 v229, s25, v189
	v_lshlrev_b32_e32 v230, s25, v190
	v_lshlrev_b32_e32 v231, s25, v191
	s_mov_b32 s25, 2
	s_branch .LBB0_427

; template <bool CLAMP>
; __device__ __forceinline__ void load_k(bf16x8 (&kf)[4], const bf16_t* kbase, int k0, int kst, const WaveCtx& c) {
;     int kp = k0 + kst * c.q; if (CLAMP) kp = kp < 0 ? 0 : (kp > SEQ - 1 ? SEQ - 1 : kp);
;     const bf16_t* kr = kbase + (size_t)kp * LDQ + 8 * c.h;
; #pragma unroll
;     for (int ks = 0; ks < 4; ++ks) kf[ks] = *(const bf16x8*)(kr + 16 * ks);
; }
; template <bool CLAMP>
; __device__ __forceinline__ void load_v(u32x4 (&vr)[4], const bf16_t* vbase, int k0, int kst, const WaveCtx& c) {
; #pragma unroll
;     for (int i = 0; i < 4; ++i) { const int p = c.lane + 64 * i, n = p >> 3; int kp = k0 + kst * n; if (CLAMP) kp = kp < 0 ? 0 : (kp > SEQ - 1 ? SEQ - 1 : kp);
;         vr[i] = *(const u32x4*)(vbase + (size_t)kp * LDQ + (p & 7) * 8); }
; __device__ __forceinline__ void unit_A2(const bf16_t* qkv, bf16_t* outA, int b, int slot, int blk, int w, LAS unsigned char* lds, const WaveCtx& c) {
;     ...
;         for (int i = 0; i < ntot; i += 2) {
;             if (i + 1 < ntot) issue_kv<true>(tb, kbase, vbase, A_K0(i + 1), dil, c);
;             soft_compute<0>(st, qf, ta, A_K0(i), dil, qp, W, dil - 1, true, false, c);
.LBB0_427:
	s_add_i32 s26, s25, -1
	s_cmp_lt_i32 s26, s9
	s_cselect_b64 s[6:7], -1, 0
	s_cmp_ge_i32 s26, s9
	s_cbranch_scc1 .LBB0_429
	s_cmp_lt_i32 s26, s8
	s_cselect_b32 s0, 0, s8
	s_cselect_b32 s1, s20, s21
	s_not_b32 s0, s0
	s_add_i32 s0, s0, s25
	s_lshl_b32 s0, s0, s22
	s_add_i32 s0, s0, s1
	v_add_u32_e32 v48, s0, v217
	v_med3_i32 v48, v48, 0, v243
	v_mul_u32_u24_e32 v64, 0x1200, v48
	v_lshl_add_u64 v[48:49], v[64:65], 1, v[166:167]
	global_load_dwordx4 v[66:69], v[48:49], off offset:3072
	global_load_dwordx4 v[70:73], v[48:49], off offset:3104
	global_load_dwordx4 v[74:77], v[48:49], off offset:3136
	global_load_dwordx4 v[78:81], v[48:49], off offset:3168
	v_add_u32_e32 v48, s0, v201
	v_med3_i32 v48, v48, 0, v243
	v_add_u32_e32 v50, s0, v200
	v_mul_u32_u24_e32 v64, 0x1200, v48
	v_med3_i32 v50, v50, 0, v243
	v_lshl_add_u64 v[48:49], v[64:65], 1, v[168:169]
	v_mul_u32_u24_e32 v64, 0x1200, v50
	v_lshl_add_u64 v[50:51], v[64:65], 1, v[168:169]
	global_load_dwordx4 v[82:85], v[48:49], off
	global_load_dwordx4 v[86:89], v[50:51], off
	v_add_u32_e32 v48, s0, v199
	v_med3_i32 v48, v48, 0, v243
	v_add_u32_e32 v50, s0, v198
	v_mul_u32_u24_e32 v64, 0x1200, v48
	v_med3_i32 v50, v50, 0, v243
	v_lshl_add_u64 v[48:49], v[64:65], 1, v[168:169]
	v_mul_u32_u24_e32 v64, 0x1200, v50
	v_lshl_add_u64 v[50:51], v[64:65], 1, v[168:169]
	global_load_dwordx4 v[90:93], v[48:49], off
	global_load_dwordx4 v[94:97], v[50:51], off
	s_waitcnt vmcnt(8) lgkmcnt(0)
	s_branch .Lgo_429

; __device__ __forceinline__ float xor32_max(float v) { auto rr = __builtin_amdgcn_permlane32_swap(__float_as_uint(v), __float_as_uint(v), false, false); return fmaxf(__uint_as_float(rr[0]), __uint_as_float(rr[1])); }
; __device__ __forceinline__ int crow(int r, int h) { return (r & 3) + 8 * (r >> 2) + 4 * h; }
; template <int MODE>
; __device__ __forceinline__ void soft_compute(SoftState& st, const bf16x8 (&qf)[4], const KV& t, int k0, int kst, int qp, int W, int dilm1, bool lane_ok, bool diag, const WaveCtx& c) {
;     store_v(t.vr, c);
;     VF vf; read_vf(vf, c);
;     f32x16 s = qk_ref(t.kf, qf, st.negm);
;     if (MODE == 0) {
;         const int relb = qp - k0;
;         const bool cls_ok = ((relb & dilm1) == 0);
; #pragma unroll
;         for (int r = 0; r < 16; ++r) {
;             const unsigned rel = (unsigned)(relb - kst * crow(r, c.h));
;             s[r] = (cls_ok && rel <= (unsigned)W) ? s[r] : -1e30f;
;         }
;     } else if (diag) {
; #pragma unroll
;         for (int r = 0; r < 16; ++r) { const int kp = k0 + crow(r, c.h); s[r] = (kp <= qp) ? s[r] : -1e30f; }
;     } else if (__ballot(!lane_ok) != 0ull) {
; #pragma unroll
;         for (int r = 0; r < 16; ++r) s[r] = lane_ok ? s[r] : -1e30f;
;     }
;     float mx = fmaxf(fmaxf(s[0], s[1]), fmaxf(s[2], s[3]));
; #pragma unroll
;     for (int r = 4; r < 16; r += 4) mx = fmaxf(mx, fmaxf(fmaxf(s[r], s[r + 1]), fmaxf(s[r + 2], s[r + 3])));
;     mx = xor32_max(mx);
;     if (__ballot(mx > 8.0f) != 0ull) {
;         const float d = fmaxf(mx, 0.f), scl = __builtin_amdgcn_exp2f(-d);
;         st.l *= scl; st.m += d;
;         const float nm = -st.m;
; #pragma unroll
;         for (int r = 0; r < 16; ++r) { st.o[0][r] *= scl; st.o[1][r] *= scl; s[r] -= d; st.negm[r] = nm; }
.Lgo_429:
	v_mfma_f32_32x32x16_bf16 v[48:63], v[142:145], v[98:101], v[32:47]
	s_add_i32 s0, s25, -2
	s_cmp_lt_i32 s0, s8
	s_cselect_b32 s0, 0, s8
	s_cselect_b32 s1, s20, s21
	s_add_i32 s0, s0, s24
	s_lshl_b32 s0, s0, s22
	v_subrev_u32_e32 v64, s1, v172
	v_mfma_f32_32x32x16_bf16 v[48:63], v[134:137], v[102:105], v[48:63]
	v_add_u32_e32 v202, s0, v64
	v_and_b32_e32 v64, s23, v202
	v_cmp_eq_u32_e32 vcc, 0, v64
	v_sub_u32_e32 v64, v202, v165
	v_cmp_ge_u32_e64 s[0:1], s19, v64
	v_add_u32_e32 v203, v202, v195
	s_and_b64 s[0:1], vcc, s[0:1]
	v_mfma_f32_32x32x16_bf16 v[48:63], v[126:129], v[106:109], v[48:63]
	v_add_u32_e32 v248, v176, v196
	ds_write_b128 v248, v[138:141]
	ds_write_b128 v192, v[130:133]
	ds_write_b128 v193, v[118:121]
	ds_write_b128 v197, v[114:117]
	v_add_u32_e32 v247, s12, v215
	ds_read_b64_tr_b16 v[158:159], v247
	ds_read_b64_tr_b16 v[160:161], v247 offset:1152
	ds_read_b64_tr_b16 v[156:157], v247 offset:1216
	ds_read_b64_tr_b16 v[154:155], v247 offset:64
	ds_read_b64_tr_b16 v[150:151], v247 offset:2304
	ds_read_b64_tr_b16 v[152:153], v247 offset:3456
	ds_read_b64_tr_b16 v[148:149], v247 offset:3520
	ds_read_b64_tr_b16 v[146:147], v247 offset:2368
	v_mfma_f32_32x32x16_bf16 v[48:63], v[122:125], v[110:113], v[48:63]
	s_nop 11
	v_cndmask_b32_e64 v64, v244, v48, s[0:1]
	v_cmp_ge_u32_e64 s[0:1], s19, v203
	s_and_b64 s[0:1], vcc, s[0:1]
	v_sub_u32_e32 v48, v202, v218
	v_cndmask_b32_e64 v249, v244, v49, s[0:1]
	v_cmp_ge_u32_e64 s[0:1], s19, v48
	s_and_b64 s[0:1], vcc, s[0:1]
	v_sub_u32_e32 v48, v202, v219
	v_cndmask_b32_e64 v250, v244, v50, s[0:1]
	v_cmp_ge_u32_e64 s[0:1], s19, v48
	s_and_b64 s[0:1], vcc, s[0:1]
	v_sub_u32_e32 v48, v202, v220
	v_cndmask_b32_e64 v251, v244, v51, s[0:1]
	v_cmp_ge_u32_e64 s[0:1], s19, v48
	s_and_b64 s[0:1], vcc, s[0:1]
	v_sub_u32_e32 v48, v202, v221
	v_cndmask_b32_e64 v252, v244, v52, s[0:1]
	v_cmp_ge_u32_e64 s[0:1], s19, v48
	s_and_b64 s[0:1], vcc, s[0:1]
	v_sub_u32_e32 v48, v202, v222
	v_cndmask_b32_e64 v53, v244, v53, s[0:1]
	v_cmp_ge_u32_e64 s[0:1], s19, v48
	s_and_b64 s[0:1], vcc, s[0:1]
	v_sub_u32_e32 v48, v202, v223
	v_cndmask_b32_e64 v54, v244, v54, s[0:1]
	v_cmp_ge_u32_e64 s[0:1], s19, v48
	s_and_b64 s[0:1], vcc, s[0:1]
	v_sub_u32_e32 v48, v202, v224
	v_cndmask_b32_e64 v55, v244, v55, s[0:1]
	v_cmp_ge_u32_e64 s[0:1], s19, v48
	s_and_b64 s[0:1], vcc, s[0:1]
	v_sub_u32_e32 v48, v202, v225
	v_cndmask_b32_e64 v253, v244, v56, s[0:1]
	v_cmp_ge_u32_e64 s[0:1], s19, v48
	s_and_b64 s[0:1], vcc, s[0:1]
	v_sub_u32_e32 v48, v202, v226
	v_cndmask_b32_e64 v56, v244, v57, s[0:1]
	v_cmp_ge_u32_e64 s[0:1], s19, v48
	s_and_b64 s[0:1], vcc, s[0:1]
	v_sub_u32_e32 v48, v202, v227
	v_cndmask_b32_e64 v57, v244, v58, s[0:1]
	v_cmp_ge_u32_e64 s[0:1], s19, v48
	s_and_b64 s[0:1], vcc, s[0:1]
	v_sub_u32_e32 v49, v202, v228
	v_cndmask_b32_e64 v48, v244, v59, s[0:1]
	v_cmp_ge_u32_e64 s[0:1], s19, v49
	s_and_b64 s[0:1], vcc, s[0:1]
	v_sub_u32_e32 v50, v202, v229
	v_cndmask_b32_e64 v49, v244, v60, s[0:1]
	v_cmp_ge_u32_e64 s[0:1], s19, v50
	s_and_b64 s[0:1], vcc, s[0:1]
	v_sub_u32_e32 v50, v202, v230
	v_max_f32_e32 v58, v249, v249
	v_max_f32_e32 v59, v64, v64
	v_cndmask_b32_e64 v51, v244, v61, s[0:1]
	v_cmp_ge_u32_e64 s[0:1], s19, v50
	v_max_f32_e32 v58, v59, v58
	v_max_f32_e32 v59, v251, v251
	v_max_f32_e32 v60, v250, v250
	s_and_b64 s[0:1], vcc, s[0:1]
	v_sub_u32_e32 v52, v202, v231
	v_max_f32_e32 v59, v60, v59
	v_max_f32_e32 v60, v55, v55
	v_max_f32_e32 v61, v54, v54
	v_cndmask_b32_e64 v50, v244, v62, s[0:1]
	v_cmp_ge_u32_e64 s[0:1], s19, v52
	v_max_f32_e32 v60, v61, v60
	s_and_b64 vcc, vcc, s[0:1]
	v_max3_f32 v60, v252, v53, v60
	v_cndmask_b32_e32 v52, v244, v63, vcc
	v_max3_f32 v58, v58, v59, v60
	v_max_f32_e32 v59, v48, v48
	v_max_f32_e32 v60, v57, v57
	v_max_f32_e32 v59, v60, v59
	v_max_f32_e32 v60, v52, v52
	v_max_f32_e32 v61, v50, v50
	v_max_f32_e32 v60, v61, v60
	v_max3_f32 v59, v253, v56, v59
	v_max3_f32 v60, v49, v51, v60
	v_max3_f32 v58, v58, v59, v60
	v_mov_b32_e32 v59, v58
	s_nop 1
	v_permlane32_swap_b32_e32 v58, v59
	v_max_f32_e32 v59, v59, v59
	v_max_f32_e32 v58, v58, v58
	v_max_f32_e32 v58, v58, v59
	v_cmp_lt_f32_e32 vcc, s70, v58
	s_cbranch_vccz .LBB0_431
	v_max_f32_e32 v32, v58, v58
	v_max_f32_e32 v33, 0, v32
	v_exp_f32_e64 v34, -v33
	v_add_f32_e32 v171, v171, v33
	v_xor_b32_e32 v32, 0x80000000, v171
	v_sub_f32_e32 v64, v64, v33
	v_mul_f32_e32 v170, v170, v34
	v_sub_f32_e32 v249, v249, v33
	v_sub_f32_e32 v250, v250, v33
	v_sub_f32_e32 v251, v251, v33
	v_sub_f32_e32 v252, v252, v33
	v_sub_f32_e32 v53, v53, v33
	v_sub_f32_e32 v54, v54, v33
	v_sub_f32_e32 v55, v55, v33
	v_sub_f32_e32 v253, v253, v33
	v_sub_f32_e32 v56, v56, v33
	v_sub_f32_e32 v57, v57, v33
	v_sub_f32_e32 v48, v48, v33
	v_sub_f32_e32 v49, v49, v33
	v_sub_f32_e32 v51, v51, v33
	v_sub_f32_e32 v50, v50, v33
	v_pk_mul_f32 v[30:31], v[30:31], v[34:35] op_sel_hi:[1,0]
	v_pk_mul_f32 v[28:29], v[28:29], v[34:35] op_sel_hi:[1,0]
	v_pk_mul_f32 v[26:27], v[26:27], v[34:35] op_sel_hi:[1,0]
	v_pk_mul_f32 v[24:25], v[24:25], v[34:35] op_sel_hi:[1,0]
	v_pk_mul_f32 v[22:23], v[22:23], v[34:35] op_sel_hi:[1,0]
	v_pk_mul_f32 v[20:21], v[20:21], v[34:35] op_sel_hi:[1,0]
	v_pk_mul_f32 v[18:19], v[18:19], v[34:35] op_sel_hi:[1,0]
	v_pk_mul_f32 v[16:17], v[16:17], v[34:35] op_sel_hi:[1,0]
	v_pk_mul_f32 v[14:15], v[14:15], v[34:35] op_sel_hi:[1,0]
	v_pk_mul_f32 v[12:13], v[12:13], v[34:35] op_sel_hi:[1,0]
	v_pk_mul_f32 v[10:11], v[10:11], v[34:35] op_sel_hi:[1,0]
	v_pk_mul_f32 v[8:9], v[8:9], v[34:35] op_sel_hi:[1,0]
	v_pk_mul_f32 v[6:7], v[6:7], v[34:35] op_sel_hi:[1,0]
	v_pk_mul_f32 v[4:5], v[4:5], v[34:35] op_sel_hi:[1,0]
	v_pk_mul_f32 v[2:3], v[2:3], v[34:35] op_sel_hi:[1,0]
	v_pk_mul_f32 v[0:1], v[0:1], v[34:35] op_sel_hi:[1,0]
	v_sub_f32_e32 v52, v52, v33
	v_mov_b32_e32 v33, v32
	v_mov_b32_e32 v34, v32
	v_mov_b32_e32 v35, v32
	v_mov_b32_e32 v36, v32
	v_mov_b32_e32 v37, v32
	v_mov_b32_e32 v38, v32
	v_mov_b32_e32 v39, v32
	v_mov_b32_e32 v40, v32
	v_mov_b32_e32 v41, v32
	v_mov_b32_e32 v42, v32
	v_mov_b32_e32 v43, v32
	v_mov_b32_e32 v44, v32
	v_mov_b32_e32 v45, v32
	v_mov_b32_e32 v46, v32
	v_mov_b32_e32 v47, v32
; __device__ __forceinline__ float xor32_sum(float v) { auto rr = __builtin_amdgcn_permlane32_swap(__float_as_uint(v), __float_as_uint(v), false, false); return __uint_as_float(rr[0]) + __uint_as_float(rr[1]); }
; template <int MODE>
; __device__ __forceinline__ void soft_compute(SoftState& st, const bf16x8 (&qf)[4], const KV& t, int k0, int kst, int qp, int W, int dilm1, bool lane_ok, bool diag, const WaveCtx& c) {
;     ...
;     float ps = 0.f;
; #pragma unroll
;     for (int r = 0; r < 16; ++r) { const float p = __builtin_amdgcn_exp2f(s[r]); s[r] = p; ps += p; }
;     st.l += xor32_sum(ps);
;     pv(st.o, s, vf);
; __device__ __forceinline__ void unit_A2(const bf16_t* qkv, bf16_t* outA, int b, int slot, int blk, int w, LAS unsigned char* lds, const WaveCtx& c) {
;     ...
;             if (i + 1 >= ntot) break;
;             if (i + 2 < ntot) issue_kv<true>(ta, kbase, vbase, A_K0(i + 2), dil, c);
.LBB0_431:
	v_exp_f32_e32 v58, v64
	v_exp_f32_e32 v59, v249
	v_exp_f32_e32 v60, v250
	v_exp_f32_e32 v61, v251
	v_add_f32_e32 v62, 0, v58
	v_exp_f32_e32 v63, v252
	v_add_f32_e32 v62, v59, v62
	v_exp_f32_e32 v53, v53
	v_add_f32_e32 v62, v60, v62
	v_exp_f32_e32 v64, v54
	v_add_f32_e32 v62, v61, v62
	v_exp_f32_e32 v202, v55
	v_add_f32_e32 v62, v63, v62
	v_exp_f32_e32 v203, v253
	v_add_f32_e32 v54, v53, v62
	v_add_f32_e32 v54, v64, v54
	v_add_f32_e32 v54, v202, v54
	v_add_f32_e32 v62, v203, v54
	v_exp_f32_e32 v206, v56
	v_exp_f32_e32 v207, v57
	v_cvt_pk_bf16_f32 v54, v58, v59
	v_cvt_pk_bf16_f32 v55, v60, v61
	v_cvt_pk_bf16_f32 v56, v63, v53
	v_cvt_pk_bf16_f32 v57, v64, v202
	v_exp_f32_e32 v58, v48
	v_exp_f32_e32 v59, v49
	s_waitcnt lgkmcnt(6)
	v_mfma_f32_32x32x16_bf16 v[16:31], v[158:161], v[54:57], v[16:31]
	v_add_f32_e32 v53, v206, v62
	v_exp_f32_e32 v51, v51
	v_exp_f32_e32 v52, v52
	v_add_f32_e32 v48, v207, v53
	v_add_f32_e32 v48, v58, v48
	v_add_f32_e32 v48, v59, v48
	v_add_f32_e32 v53, v51, v48
	s_waitcnt lgkmcnt(4)
	v_mfma_f32_32x32x16_bf16 v[0:15], v[154:157], v[54:57], v[0:15]
	v_exp_f32_e32 v54, v50
	v_cvt_pk_bf16_f32 v48, v203, v206
	v_cvt_pk_bf16_f32 v49, v207, v58
	v_cvt_pk_bf16_f32 v50, v59, v51
	v_cvt_pk_bf16_f32 v51, v54, v52
	v_add_f32_e32 v53, v54, v53
	v_add_f32_e32 v52, v52, v53
	s_waitcnt lgkmcnt(2)
	v_mfma_f32_32x32x16_bf16 v[16:31], v[150:153], v[48:51], v[16:31]
	v_mov_b32_e32 v53, v52
	s_nop 1
	v_permlane32_swap_b32_e32 v52, v53
	v_add_f32_e32 v52, v52, v53
	v_add_f32_e32 v170, v170, v52
	s_andn2_b64 vcc, exec, s[6:7]
	s_mov_b64 s[6:7], -1
	s_waitcnt lgkmcnt(0)
	v_mfma_f32_32x32x16_bf16 v[0:15], v[146:149], v[48:51], v[0:15]
	s_cbranch_vccnz .LBB0_426
	s_cmp_ge_i32 s25, s9
	s_cselect_b64 s[6:7], -1, 0
	s_and_b64 vcc, exec, s[6:7]
	s_cbranch_vccnz .LBB0_434
	s_cmp_lt_i32 s25, s8
	s_cselect_b32 s0, 0, s8
	s_cselect_b32 s1, s20, s21
	s_sub_i32 s0, s25, s0
	s_lshl_b32 s0, s0, s22
	s_add_i32 s0, s0, s1
	v_add_u32_e32 v48, s0, v217
	v_med3_i32 v48, v48, 0, v243
	v_mul_u32_u24_e32 v64, 0x1200, v48
	v_lshl_add_u64 v[48:49], v[64:65], 1, v[166:167]
	global_load_dwordx4 v[142:145], v[48:49], off offset:3072
	global_load_dwordx4 v[134:137], v[48:49], off offset:3104
	global_load_dwordx4 v[126:129], v[48:49], off offset:3136
	global_load_dwordx4 v[122:125], v[48:49], off offset:3168
	v_add_u32_e32 v48, s0, v201
	v_med3_i32 v48, v48, 0, v243
	v_add_u32_e32 v50, s0, v200
	v_mul_u32_u24_e32 v64, 0x1200, v48
	v_med3_i32 v50, v50, 0, v243
	v_lshl_add_u64 v[48:49], v[64:65], 1, v[168:169]
	v_mul_u32_u24_e32 v64, 0x1200, v50
	v_lshl_add_u64 v[50:51], v[64:65], 1, v[168:169]
	global_load_dwordx4 v[138:141], v[48:49], off
	global_load_dwordx4 v[130:133], v[50:51], off
	v_add_u32_e32 v48, s0, v199
	v_med3_i32 v48, v48, 0, v243
	v_add_u32_e32 v50, s0, v198
	v_mul_u32_u24_e32 v64, 0x1200, v48
	v_med3_i32 v50, v50, 0, v243
	v_lshl_add_u64 v[48:49], v[64:65], 1, v[168:169]
	v_mul_u32_u24_e32 v64, 0x1200, v50
	v_lshl_add_u64 v[50:51], v[64:65], 1, v[168:169]
	global_load_dwordx4 v[118:121], v[48:49], off
	global_load_dwordx4 v[114:117], v[50:51], off
	s_waitcnt vmcnt(8)
	s_branch .Lgo_434
.LBB0_434:
	s_waitcnt vmcnt(0)
; __device__ __forceinline__ float xor32_max(float v) { auto rr = __builtin_amdgcn_permlane32_swap(__float_as_uint(v), __float_as_uint(v), false, false); return fmaxf(__uint_as_float(rr[0]), __uint_as_float(rr[1])); }
; __device__ __forceinline__ int crow(int r, int h) { return (r & 3) + 8 * (r >> 2) + 4 * h; }
; template <int MODE>
; __device__ __forceinline__ void soft_compute(SoftState& st, const bf16x8 (&qf)[4], const KV& t, int k0, int kst, int qp, int W, int dilm1, bool lane_ok, bool diag, const WaveCtx& c) {
;     store_v(t.vr, c);
;     VF vf; read_vf(vf, c);
;     f32x16 s = qk_ref(t.kf, qf, st.negm);
;     if (MODE == 0) {
;         const int relb = qp - k0;
;         const bool cls_ok = ((relb & dilm1) == 0);
; #pragma unroll
;         for (int r = 0; r < 16; ++r) {
;             const unsigned rel = (unsigned)(relb - kst * crow(r, c.h));
;             s[r] = (cls_ok && rel <= (unsigned)W) ? s[r] : -1e30f;
;         }
;     } else if (diag) {
; #pragma unroll
;         for (int r = 0; r < 16; ++r) { const int kp = k0 + crow(r, c.h); s[r] = (kp <= qp) ? s[r] : -1e30f; }
;     } else if (__ballot(!lane_ok) != 0ull) {
; #pragma unroll
;         for (int r = 0; r < 16; ++r) s[r] = lane_ok ? s[r] : -1e30f;
;     }
;     float mx = fmaxf(fmaxf(s[0], s[1]), fmaxf(s[2], s[3]));
; #pragma unroll
;     for (int r = 4; r < 16; r += 4) mx = fmaxf(mx, fmaxf(fmaxf(s[r], s[r + 1]), fmaxf(s[r + 2], s[r + 3])));
;     mx = xor32_max(mx);
;     if (__ballot(mx > 8.0f) != 0ull) {
;         const float d = fmaxf(mx, 0.f), scl = __builtin_amdgcn_exp2f(-d);
;         st.l *= scl; st.m += d;
;         const float nm = -st.m;
; #pragma unroll
;         for (int r = 0; r < 16; ++r) { st.o[0][r] *= scl; st.o[1][r] *= scl; s[r] -= d; st.negm[r] = nm; }
.Lgo_434:
	v_mfma_f32_32x32x16_bf16 v[48:63], v[66:69], v[98:101], v[32:47]
	s_cmp_lt_i32 s26, s8
	s_cselect_b32 s0, 0, s8
	s_cselect_b32 s1, s20, s21
	s_add_i32 s0, s0, s24
	s_add_i32 s0, s0, -1
	s_lshl_b32 s0, s0, s22
	v_subrev_u32_e32 v64, s1, v172
	v_mfma_f32_32x32x16_bf16 v[48:63], v[70:73], v[102:105], v[48:63]
	v_add_u32_e32 v202, s0, v64
	v_and_b32_e32 v64, s23, v202
	v_cmp_eq_u32_e32 vcc, 0, v64
	v_sub_u32_e32 v64, v202, v165
	v_cmp_ge_u32_e64 s[0:1], s19, v64
	s_and_b64 s[0:1], vcc, s[0:1]
	ds_write_b128 v248, v[82:85]
	ds_write_b128 v192, v[86:89]
	ds_write_b128 v193, v[90:93]
	ds_write_b128 v197, v[94:97]
	v_mfma_f32_32x32x16_bf16 v[48:63], v[74:77], v[106:109], v[48:63]
	ds_read_b64_tr_b16 v[158:159], v247
	ds_read_b64_tr_b16 v[160:161], v247 offset:1152
	ds_read_b64_tr_b16 v[150:151], v247 offset:2304
	ds_read_b64_tr_b16 v[152:153], v247 offset:3456
	ds_read_b64_tr_b16 v[154:155], v247 offset:64
	ds_read_b64_tr_b16 v[156:157], v247 offset:1216
	ds_read_b64_tr_b16 v[146:147], v247 offset:2368
	ds_read_b64_tr_b16 v[148:149], v247 offset:3520
	v_mfma_f32_32x32x16_bf16 v[48:63], v[78:81], v[110:113], v[48:63]
	s_nop 11
	v_cndmask_b32_e64 v64, v244, v48, s[0:1]
	v_add_u32_e32 v48, v202, v195
	v_cmp_ge_u32_e64 s[0:1], s19, v48
	s_and_b64 s[0:1], vcc, s[0:1]
	v_sub_u32_e32 v48, v202, v218
	v_cndmask_b32_e64 v247, v244, v49, s[0:1]
	v_cmp_ge_u32_e64 s[0:1], s19, v48
	s_and_b64 s[0:1], vcc, s[0:1]
	v_sub_u32_e32 v48, v202, v219
	v_cndmask_b32_e64 v248, v244, v50, s[0:1]
	v_cmp_ge_u32_e64 s[0:1], s19, v48
	s_and_b64 s[0:1], vcc, s[0:1]
	v_sub_u32_e32 v48, v202, v220
	v_cndmask_b32_e64 v249, v244, v51, s[0:1]
	v_cmp_ge_u32_e64 s[0:1], s19, v48
	s_and_b64 s[0:1], vcc, s[0:1]
	v_sub_u32_e32 v48, v202, v221
	v_cndmask_b32_e64 v250, v244, v52, s[0:1]
	v_cmp_ge_u32_e64 s[0:1], s19, v48
	s_and_b64 s[0:1], vcc, s[0:1]
	v_sub_u32_e32 v48, v202, v222
	v_cndmask_b32_e64 v53, v244, v53, s[0:1]
	v_cmp_ge_u32_e64 s[0:1], s19, v48
	s_and_b64 s[0:1], vcc, s[0:1]
	v_sub_u32_e32 v48, v202, v223
	v_cndmask_b32_e64 v54, v244, v54, s[0:1]
	v_cmp_ge_u32_e64 s[0:1], s19, v48
	s_and_b64 s[0:1], vcc, s[0:1]
	v_sub_u32_e32 v48, v202, v224
	v_cndmask_b32_e64 v55, v244, v55, s[0:1]
	v_cmp_ge_u32_e64 s[0:1], s19, v48
	s_and_b64 s[0:1], vcc, s[0:1]
	v_sub_u32_e32 v48, v202, v225
	v_cndmask_b32_e64 v251, v244, v56, s[0:1]
	v_cmp_ge_u32_e64 s[0:1], s19, v48
	s_and_b64 s[0:1], vcc, s[0:1]
	v_sub_u32_e32 v48, v202, v226
	v_cndmask_b32_e64 v56, v244, v57, s[0:1]
	v_cmp_ge_u32_e64 s[0:1], s19, v48
	s_and_b64 s[0:1], vcc, s[0:1]
	v_sub_u32_e32 v48, v202, v227
	v_cndmask_b32_e64 v57, v244, v58, s[0:1]
	v_cmp_ge_u32_e64 s[0:1], s19, v48
	s_and_b64 s[0:1], vcc, s[0:1]
	v_sub_u32_e32 v49, v202, v228
	v_cndmask_b32_e64 v48, v244, v59, s[0:1]
	v_cmp_ge_u32_e64 s[0:1], s19, v49
	s_and_b64 s[0:1], vcc, s[0:1]
	v_sub_u32_e32 v50, v202, v229
	v_cndmask_b32_e64 v49, v244, v60, s[0:1]
	v_cmp_ge_u32_e64 s[0:1], s19, v50
	s_and_b64 s[0:1], vcc, s[0:1]
	v_sub_u32_e32 v50, v202, v230
	v_max_f32_e32 v58, v247, v247
	v_max_f32_e32 v59, v64, v64
	v_cndmask_b32_e64 v51, v244, v61, s[0:1]
	v_cmp_ge_u32_e64 s[0:1], s19, v50
	v_max_f32_e32 v58, v59, v58
	v_max_f32_e32 v59, v249, v249
	v_max_f32_e32 v60, v248, v248
	s_and_b64 s[0:1], vcc, s[0:1]
	v_sub_u32_e32 v52, v202, v231
	v_max_f32_e32 v59, v60, v59
	v_max_f32_e32 v60, v55, v55
	v_max_f32_e32 v61, v54, v54
	v_cndmask_b32_e64 v50, v244, v62, s[0:1]
	v_cmp_ge_u32_e64 s[0:1], s19, v52
	v_max_f32_e32 v60, v61, v60
	s_and_b64 vcc, vcc, s[0:1]
	v_max3_f32 v60, v250, v53, v60
	v_cndmask_b32_e32 v52, v244, v63, vcc
	v_max3_f32 v58, v58, v59, v60
	v_max_f32_e32 v59, v48, v48
	v_max_f32_e32 v60, v57, v57
	v_max_f32_e32 v59, v60, v59
	v_max_f32_e32 v60, v52, v52
	v_max_f32_e32 v61, v50, v50
	v_max_f32_e32 v60, v61, v60
	v_max3_f32 v59, v251, v56, v59
	v_max3_f32 v60, v49, v51, v60
	v_max3_f32 v58, v58, v59, v60
	v_mov_b32_e32 v59, v58
	s_nop 1
	v_permlane32_swap_b32_e32 v58, v59
	v_max_f32_e32 v59, v59, v59
	v_max_f32_e32 v58, v58, v58
	v_max_f32_e32 v58, v58, v59
	v_cmp_lt_f32_e32 vcc, s70, v58
	s_cbranch_vccz .LBB0_436
	v_max_f32_e32 v32, v58, v58
	v_max_f32_e32 v33, 0, v32
	v_exp_f32_e64 v34, -v33
	v_add_f32_e32 v171, v171, v33
	v_xor_b32_e32 v32, 0x80000000, v171
	v_sub_f32_e32 v64, v64, v33
	v_mul_f32_e32 v170, v170, v34
	v_sub_f32_e32 v247, v247, v33
	v_sub_f32_e32 v248, v248, v33
	v_sub_f32_e32 v249, v249, v33
	v_sub_f32_e32 v250, v250, v33
	v_sub_f32_e32 v53, v53, v33
	v_sub_f32_e32 v54, v54, v33
	v_sub_f32_e32 v55, v55, v33
	v_sub_f32_e32 v251, v251, v33
	v_sub_f32_e32 v56, v56, v33
	v_sub_f32_e32 v57, v57, v33
	v_sub_f32_e32 v48, v48, v33
	v_sub_f32_e32 v49, v49, v33
	v_sub_f32_e32 v51, v51, v33
	v_sub_f32_e32 v50, v50, v33
	v_pk_mul_f32 v[30:31], v[30:31], v[34:35] op_sel_hi:[1,0]
	v_pk_mul_f32 v[28:29], v[28:29], v[34:35] op_sel_hi:[1,0]
	v_pk_mul_f32 v[26:27], v[26:27], v[34:35] op_sel_hi:[1,0]
	v_pk_mul_f32 v[24:25], v[24:25], v[34:35] op_sel_hi:[1,0]
	v_pk_mul_f32 v[22:23], v[22:23], v[34:35] op_sel_hi:[1,0]
	v_pk_mul_f32 v[20:21], v[20:21], v[34:35] op_sel_hi:[1,0]
	v_pk_mul_f32 v[18:19], v[18:19], v[34:35] op_sel_hi:[1,0]
	v_pk_mul_f32 v[16:17], v[16:17], v[34:35] op_sel_hi:[1,0]
	v_pk_mul_f32 v[14:15], v[14:15], v[34:35] op_sel_hi:[1,0]
	v_pk_mul_f32 v[12:13], v[12:13], v[34:35] op_sel_hi:[1,0]
	v_pk_mul_f32 v[10:11], v[10:11], v[34:35] op_sel_hi:[1,0]
	v_pk_mul_f32 v[8:9], v[8:9], v[34:35] op_sel_hi:[1,0]
	v_pk_mul_f32 v[6:7], v[6:7], v[34:35] op_sel_hi:[1,0]
	v_pk_mul_f32 v[4:5], v[4:5], v[34:35] op_sel_hi:[1,0]
	v_pk_mul_f32 v[2:3], v[2:3], v[34:35] op_sel_hi:[1,0]
	v_pk_mul_f32 v[0:1], v[0:1], v[34:35] op_sel_hi:[1,0]
	v_sub_f32_e32 v52, v52, v33
	v_mov_b32_e32 v33, v32
	v_mov_b32_e32 v34, v32
	v_mov_b32_e32 v35, v32
	v_mov_b32_e32 v36, v32
	v_mov_b32_e32 v37, v32
	v_mov_b32_e32 v38, v32
	v_mov_b32_e32 v39, v32
	v_mov_b32_e32 v40, v32
	v_mov_b32_e32 v41, v32
	v_mov_b32_e32 v42, v32
	v_mov_b32_e32 v43, v32
	v_mov_b32_e32 v44, v32
	v_mov_b32_e32 v45, v32
	v_mov_b32_e32 v46, v32
	v_mov_b32_e32 v47, v32

; __device__ __forceinline__ void unit_C(const bf16_t* qkv, bf16_t* outC, int b, int hc, int qt, const WaveCtx& c) {
;     const int qp = 32 * qt + c.q, head = 18 + hc;
;     const bf16_t* rowb = qkv + (size_t)b * SEQ * LDQ;
;     bf16x8 qf[4]; load_q(qf, rowb + (size_t)qp * LDQ + head * 64, c.h);
;     const bf16_t* kbase = rowb + MIXW + head * 64; const bf16_t* vbase = rowb + 2 * MIXW + head * 64;
;     f32x16 o[2];
; #pragma unroll
;     for (int r = 0; r < 16; ++r) { o[0][r] = 0.f; o[1][r] = 0.f; }
;     float carry = 0.f;
;     KV ta, tb;
;     issue_kv<false>(ta, kbase, vbase, 32 * qt, 1, c);
; __device__ __forceinline__ void attn_phase(const Params& p, unsigned char* ws, int layer, LAS unsigned char* lds, const int tid, int rep) {
;     ...
;         if (u >= 640u) break;
;         const int wgu = (int)(u >> 3) * 8 + qid, sub = (int)(u & 7);
;         if (wgu < 256) { unit_A(qkv, outA, wgu >> 5, (wgu & 31) >> 3, wgu & 7, sub, c); }
;         else { const int w2 = wgu - 256, qb = 7 - w2 / 48, r2 = w2 % 48; unit_C(qkv, outC, r2 / 6, r2 % 6, qb * 8 + sub, c); }
.LBB0_590:
	s_or_b64 exec, exec, s[0:1]
	s_waitcnt vmcnt(0) lgkmcnt(0)
	v_readfirstlane_b32 s6, v1
	s_add_i32 s7, s6, 0x100
	s_and_b64 s[0:1], s[62:63], exec
	s_cselect_b32 s11, s7, s6
	s_cmpk_gt_u32 s11, 0x27f
	s_mov_b64 s[0:1], -1
	s_cbranch_scc1 .LBB0_587
	v_and_b32_e32 v174, 31, v0
	v_lshrrev_b32_e32 v166, 5, v168
	v_lshrrev_b32_e32 v167, 2, v0
	v_and_b32_e32 v1, 16, v0
	v_lshlrev_b32_e32 v0, 2, v0
	v_lshlrev_b32_e32 v164, 2, v166
	v_and_or_b32 v0, v0, 12, v1
	v_and_or_b32 v2, v167, 3, v164
	v_lshlrev_b32_e32 v0, 1, v0
	s_and_b32 s6, s11, 0x3f8
	v_mad_u32_u24 v175, v2, s58, v0
	s_cmpk_gt_u32 s6, 0xff
	s_cbranch_scc0 .LBB0_603
	s_or_b32 s0, s6, s68
	s_addk_i32 s0, 0xff00
	s_mul_hi_u32 s1, s0, 0xaaaaaaab
	s_lshr_b32 s16, s1, 5
	s_mul_i32 s1, s16, 48
	s_sub_i32 s0, s0, s1
	s_mul_i32 s1, s0, 0xab
	s_bfe_u32 s12, s1, 0x6000a
	s_mul_i32 s1, s12, 6
	s_sub_i32 s0, s0, s1
	s_and_b32 s15, s11, 7
	s_and_b32 s8, s0, 0xff
	s_lshl_b32 s0, s16, 3
	s_sub_i32 s14, s15, s0
	s_add_i32 s14, s14, 56
	s_lshl_b32 s17, s14, 5
	s_mul_i32 s0, s12, 0x1200000
	s_add_u32 s0, s84, s0
	s_addc_u32 s1, s85, 0
	v_or_b32_e32 v165, s17, v174
	v_mov_b64_e32 v[0:1], s[0:1]
	v_mad_u64_u32 v[0:1], s[6:7], v165, s71, v[0:1]
	s_lshl_b32 s13, s8, 6
	s_lshl_b32 s80, s8, 7
	v_lshl_add_u64 v[0:1], v[0:1], 0, s[80:81]
	v_lshlrev_b32_e32 v64, 4, v166
	s_add_u32 s6, s0, 0xc00
	v_lshl_add_u64 v[0:1], v[0:1], 0, v[64:65]
	s_addc_u32 s7, s1, 0
	global_load_dwordx4 v[66:69], v[0:1], off offset:2304
	global_load_dwordx4 v[70:73], v[0:1], off offset:2336
	global_load_dwordx4 v[74:77], v[0:1], off offset:2368
	global_load_dwordx4 v[78:81], v[0:1], off offset:2400
	v_mov_b64_e32 v[0:1], s[6:7]
	s_add_u32 s0, s0, 0x1800
	v_mad_u64_u32 v[0:1], s[8:9], v165, s71, v[0:1]
	s_addc_u32 s1, s1, 0
	v_lshl_add_u64 v[0:1], v[0:1], 0, v[64:65]
	s_addk_i32 s80, 0x900
	v_lshl_add_u64 v[0:1], v[0:1], 0, s[80:81]
	v_lshrrev_b32_e32 v169, 3, v168
	global_load_dwordx4 v[82:85], v[0:1], off
	global_load_dwordx4 v[86:89], v[0:1], off offset:32
	global_load_dwordx4 v[90:93], v[0:1], off offset:64
	global_load_dwordx4 v[94:97], v[0:1], off offset:96
	v_or_b32_e32 v2, s17, v169
	v_mov_b64_e32 v[0:1], s[0:1]
	v_lshlrev_b32_e32 v4, 4, v168
	v_or_b32_e32 v170, 8, v169
	v_mad_u64_u32 v[2:3], s[8:9], v2, s71, v[0:1]
	v_and_b32_e32 v158, 0x70, v4
	v_mov_b32_e32 v159, v65
	v_or_b32_e32 v4, s17, v170
	v_lshl_add_u64 v[2:3], v[2:3], 0, v[158:159]
	v_mad_u64_u32 v[4:5], s[8:9], v4, s71, v[0:1]
	v_lshl_add_u64 v[2:3], v[2:3], 0, s[80:81]
	v_lshl_add_u64 v[4:5], v[4:5], 0, v[158:159]
	v_or_b32_e32 v171, 16, v169
	v_lshl_add_u64 v[4:5], v[4:5], 0, s[80:81]
	global_load_dwordx4 v[98:101], v[2:3], off
	global_load_dwordx4 v[102:105], v[4:5], off
	v_or_b32_e32 v2, s17, v171
	v_or_b32_e32 v172, 24, v169
	v_mad_u64_u32 v[2:3], s[8:9], v2, s71, v[0:1]
	v_or_b32_e32 v4, s17, v172
	v_lshl_add_u64 v[2:3], v[2:3], 0, v[158:159]
	v_mad_u64_u32 v[0:1], s[8:9], v4, s71, v[0:1]
	v_lshl_add_u64 v[2:3], v[2:3], 0, s[80:81]
	v_lshl_add_u64 v[0:1], v[0:1], 0, v[158:159]
	v_lshl_add_u64 v[0:1], v[0:1], 0, s[80:81]
	global_load_dwordx4 v[106:109], v[2:3], off
	global_load_dwordx4 v[110:113], v[0:1], off
	v_mov_b32_e32 v5, s10
	v_lshl_add_u64 v[2:3], s[0:1], 0, v[158:159]
	v_mad_u32_u24 v159, v169, s58, v5
	v_lshl_add_u64 v[0:1], s[6:7], 0, v[64:65]
	v_mul_u32_u24_e32 v4, 0x90, v169
	v_add_u32_e32 v5, 0x480, v159
	v_add_u32_e32 v6, 0x900, v159
	v_add_u32_e32 v7, 0xd80, v159
	v_add_u32_e32 v8, s10, v158
	s_lshl_b32 s6, s15, 5
	s_lshl_b32 s7, s16, 8
	v_mov_b32_e32 v181, 0
	v_cmp_gt_u32_e64 s[0:1], 32, v168
	v_lshl_add_u64 v[160:161], v[0:1], 0, s[80:81]
	v_lshl_add_u64 v[162:163], v[2:3], 0, s[80:81]
	s_sub_i32 s15, s6, s7
	v_or_b32_e32 v173, 0x6e0, v174
	s_mov_b32 s16, 0
	v_add_u32_e32 v176, v8, v4
	v_add_u32_e32 v177, v5, v158
	v_add_u32_e32 v178, v6, v158
	v_add_u32_e32 v179, v7, v158
	v_mov_b32_e32 v0, 0
	v_mov_b32_e32 v1, v181
	v_mov_b32_e32 v2, v181
	v_mov_b32_e32 v3, v181
	v_mov_b32_e32 v4, v181
	v_mov_b32_e32 v5, v181
	v_mov_b32_e32 v6, v181
	v_mov_b32_e32 v7, v181
	v_mov_b32_e32 v8, v181
	v_mov_b32_e32 v9, v181
	v_mov_b32_e32 v10, v181
	v_mov_b32_e32 v11, v181
	v_mov_b32_e32 v12, v181
	v_mov_b32_e32 v13, v181
	v_mov_b32_e32 v14, v181
	v_mov_b32_e32 v15, v181
	v_mov_b32_e32 v16, 0
	v_mov_b32_e32 v17, v181
	v_mov_b32_e32 v18, v181
	v_mov_b32_e32 v19, v181
	v_mov_b32_e32 v20, v181
	v_mov_b32_e32 v21, v181
	v_mov_b32_e32 v22, v181
	v_mov_b32_e32 v23, v181
	v_mov_b32_e32 v24, v181
	v_mov_b32_e32 v25, v181
	v_mov_b32_e32 v26, v181
	v_mov_b32_e32 v27, v181
	v_mov_b32_e32 v28, v181
	v_mov_b32_e32 v29, v181
	v_mov_b32_e32 v30, v181
	v_mov_b32_e32 v31, v181
	s_branch .LBB0_595
.LBB0_593:
	s_waitcnt vmcnt(0)
.Lgo_593:
	v_mfma_f32_32x32x16_bf16 v[0:15], v[114:117], v[66:69], 0
	ds_write_b128 v176, v[130:133]
	ds_write_b128 v177, v[134:137]
	ds_write_b128 v178, v[138:141]
	ds_write_b128 v179, v[142:145]
	ds_read_b64_tr_b16 v[154:155], v180
	ds_read_b64_tr_b16 v[156:157], v180 offset:1152
	ds_read_b64_tr_b16 v[152:153], v180 offset:1216
	ds_read_b64_tr_b16 v[150:151], v180 offset:64
	ds_read_b64_tr_b16 v[146:147], v180 offset:2304
	ds_read_b64_tr_b16 v[148:149], v180 offset:3456
	v_mfma_f32_32x32x16_bf16 v[16:31], v[122:125], v[74:77], 0
	v_mfma_f32_32x32x16_bf16 v[0:15], v[118:121], v[70:73], v[0:15]
	v_mfma_f32_32x32x16_bf16 v[16:31], v[126:129], v[78:81], v[16:31]
	s_nop 11
	v_pk_add_f32 v[8:9], v[8:9], v[24:25]
	v_pk_add_f32 v[26:27], v[10:11], v[26:27]
	v_exp_f32_e64 v64, -|v8|
	v_exp_f32_e64 v181, -|v9|
	v_pk_add_f32 v[12:13], v[12:13], v[28:29]
	v_pk_add_f32 v[4:5], v[4:5], v[20:21]
	v_add_f32_e32 v64, 1.0, v64
	v_log_f32_e32 v186, v64
	v_add_f32_e32 v64, 1.0, v181
	v_exp_f32_e64 v181, -|v26|
	v_log_f32_e32 v190, v64
	v_exp_f32_e64 v64, -|v27|
	v_pk_add_f32 v[0:1], v[0:1], v[16:17]
	v_add_f32_e32 v181, 1.0, v181
	v_pk_add_f32 v[6:7], v[6:7], v[22:23]
	v_add_f32_e32 v64, 1.0, v64
	v_exp_f32_e64 v11, -|v0|
	v_exp_f32_e64 v23, -|v4|
	v_log_f32_e32 v187, v181
	v_exp_f32_e64 v181, -|v12|
	v_log_f32_e32 v191, v64
	v_exp_f32_e64 v64, -|v13|
	v_exp_f32_e64 v17, -|v1|
	v_exp_f32_e64 v25, -|v5|
	v_pk_add_f32 v[14:15], v[14:15], v[30:31]
	v_pk_add_f32 v[2:3], v[2:3], v[18:19]
	v_add_f32_e32 v11, 1.0, v11
	v_add_f32_e32 v23, 1.0, v23
	v_add_f32_e32 v181, 1.0, v181
	v_add_f32_e32 v64, 1.0, v64
	v_log_f32_e32 v16, v11
	v_add_f32_e32 v11, 1.0, v17
	v_exp_f32_e64 v17, -|v2|
	v_exp_f32_e64 v21, -|v3|
	v_log_f32_e32 v24, v23
	v_add_f32_e32 v23, 1.0, v25
	v_exp_f32_e64 v25, -|v6|
	v_exp_f32_e64 v31, -|v7|
	v_log_f32_e32 v194, v181
	v_exp_f32_e64 v181, -|v14|
	v_log_f32_e32 v198, v64
	v_exp_f32_e64 v64, -|v15|
	v_add_f32_e32 v17, 1.0, v17
	v_add_f32_e32 v21, 1.0, v21
	v_add_f32_e32 v25, 1.0, v25
	v_add_f32_e32 v31, 1.0, v31
	v_add_f32_e32 v181, 1.0, v181
	v_add_f32_e32 v64, 1.0, v64
	v_log_f32_e32 v20, v11
	v_log_f32_e32 v17, v17
	v_log_f32_e32 v21, v21
	v_log_f32_e32 v30, v23
	v_log_f32_e32 v25, v25
	v_log_f32_e32 v31, v31
	v_log_f32_e32 v195, v181
	v_log_f32_e32 v199, v64
	v_max_f32_e32 v10, 0, v0
	v_max_f32_e32 v18, 0, v1
	v_max_f32_e32 v11, 0, v2
	v_max_f32_e32 v19, 0, v3
	v_max_f32_e32 v22, 0, v4
	v_max_f32_e32 v28, 0, v5
	v_max_f32_e32 v23, 0, v6
	v_max_f32_e32 v29, 0, v7
	v_max_f32_e32 v184, 0, v8
	v_max_f32_e32 v188, 0, v9
	v_max_f32_e32 v185, 0, v26
	v_max_f32_e32 v189, 0, v27
	v_max_f32_e32 v192, 0, v12
	v_max_f32_e32 v196, 0, v13
	v_max_f32_e32 v193, 0, v14
	v_max_f32_e32 v197, 0, v15
	v_pk_add_f32 v[10:11], v[10:11], v[16:17]
	v_pk_add_f32 v[16:17], v[18:19], v[20:21]
	v_pk_add_f32 v[20:21], v[22:23], v[24:25]
	v_pk_add_f32 v[22:23], v[28:29], v[30:31]
	v_pk_add_f32 v[28:29], v[184:185], v[186:187]
	v_pk_add_f32 v[30:31], v[188:189], v[190:191]
	v_pk_add_f32 v[186:187], v[192:193], v[194:195]
	v_pk_add_f32 v[188:189], v[196:197], v[198:199]
	v_sub_f32_e32 v181, v3, v17
	v_pk_add_f32 v[190:191], v[188:189], v[186:187] neg_lo:[1,1] neg_hi:[1,1]
	v_sub_f32_e32 v3, v7, v23
	v_pk_add_f32 v[190:191], v[190:191], v[190:191] op_sel:[0,1] op_sel_hi:[1,0]
	v_sub_f32_e32 v183, v27, v31
	v_sub_f32_e32 v7, v15, v189
	v_mov_b32_e32 v15, v190
	v_mov_b32_e32 v27, v190
	s_nop 1
	v_permlane32_swap_b32_e32 v15, v27
	v_cndmask_b32_e64 v191, v15, v27, s[0:1]
	v_cndmask_b32_e64 v15, 0, v191, s[0:1]
	v_add_f32_e32 v15, v182, v15
	v_mov_b32_e32 v192, v187
	v_mov_b32_e32 v193, v189
	v_pk_add_f32 v[192:193], v[14:15], v[192:193] neg_lo:[0,1] neg_hi:[0,1]
	v_pk_add_f32 v[184:185], v[30:31], v[28:29] neg_lo:[1,1] neg_hi:[1,1]
	v_mov_b32_e32 v194, v13
	v_mov_b32_e32 v195, v193
	v_mov_b32_e32 v189, v187
	v_pk_add_f32 v[194:195], v[194:195], v[188:189] neg_lo:[0,1] neg_hi:[0,1]
	v_add_f32_e32 v7, v7, v15
	v_mov_b32_e32 v14, v184
	v_mov_b32_e32 v15, v190
	v_mov_b32_e32 v190, v185
	v_exp_f32_e32 v196, v7
	v_add_f32_e32 v7, v194, v195
; __device__ __forceinline__ void unit_C(const bf16_t* qkv, bf16_t* outC, int b, int hc, int qt, const WaveCtx& c) {
;     ...
;     for (int ch = qt; ch >= 0; ch -= 2) {
;         if (ch > 0) issue_kv<false>(tb, kbase, vbase, 32 * (ch - 1), 1, c);
;         C_STEP(ta, ch);
;         if (done || ch == 0) break;
;         if (ch > 1) issue_kv<false>(ta, kbase, vbase, 32 * (ch - 2), 1, c);
	v_pk_add_f32 v[14:15], v[14:15], v[190:191]
	v_add_f32_e32 v192, v192, v193
	v_exp_f32_e32 v193, v7
	v_mov_b32_e32 v7, v14
	v_mov_b32_e32 v27, v14
	s_nop 1
	v_permlane32_swap_b32_e32 v7, v27
	v_cndmask_b32_e64 v64, v7, v27, s[0:1]
	v_mov_b32_e32 v13, v195
	v_mov_b32_e32 v187, v188
	v_pk_add_f32 v[14:15], v[14:15], v[64:65]
	v_pk_add_f32 v[12:13], v[12:13], v[186:187] neg_lo:[0,1] neg_hi:[0,1]
	v_add_f32_e32 v7, v182, v15
	v_cndmask_b32_e64 v27, 0, v64, s[0:1]
	v_add_f32_e32 v194, v12, v13
	v_mov_b32_e32 v12, v29
	v_mov_b32_e32 v13, v31
	v_add_f32_e32 v27, v27, v7
	v_pk_add_f32 v[188:189], v[26:27], v[12:13] neg_lo:[0,1] neg_hi:[0,1]
	v_mov_b32_e32 v31, v29
	v_mov_b32_e32 v12, v9
	v_mov_b32_e32 v13, v189
	v_mov_b32_e32 v29, v30
	v_pk_add_f32 v[30:31], v[12:13], v[30:31] neg_lo:[0,1] neg_hi:[0,1]
	v_pk_add_f32 v[24:25], v[22:23], v[20:21] neg_lo:[1,1] neg_hi:[1,1]
	v_mov_b32_e32 v9, v31
	v_pk_add_f32 v[28:29], v[8:9], v[28:29] neg_lo:[0,1] neg_hi:[0,1]
	v_mov_b32_e32 v8, v24
	v_mov_b32_e32 v9, v14
	v_mov_b32_e32 v14, v25
	v_pk_add_f32 v[8:9], v[8:9], v[14:15]
	v_mov_b32_e32 v14, v21
	v_mov_b32_e32 v7, v8
	v_mov_b32_e32 v12, v8
	s_nop 1
	v_permlane32_swap_b32_e32 v7, v12
	v_cndmask_b32_e64 v13, v7, v12, s[0:1]
	v_add_f32_e32 v7, v182, v9
	v_cndmask_b32_e64 v12, 0, v13, s[0:1]
	v_add_f32_e32 v7, v12, v7
	v_mov_b32_e32 v15, v23
	v_pk_add_f32 v[14:15], v[6:7], v[14:15] neg_lo:[0,1] neg_hi:[0,1]
	v_mov_b32_e32 v24, v5
	v_mov_b32_e32 v25, v15
	v_mov_b32_e32 v23, v21
	v_pk_add_f32 v[18:19], v[16:17], v[10:11] neg_lo:[1,1] neg_hi:[1,1]
	v_pk_add_f32 v[24:25], v[24:25], v[22:23] neg_lo:[0,1] neg_hi:[0,1]
	v_mov_b32_e32 v21, v22
	v_mov_b32_e32 v5, v25
	v_add_f32_e32 v3, v3, v7
	v_mov_b32_e32 v6, v18
	v_mov_b32_e32 v7, v8
	v_mov_b32_e32 v12, v19
	v_pk_add_f32 v[4:5], v[4:5], v[20:21] neg_lo:[0,1] neg_hi:[0,1]
	v_exp_f32_e32 v20, v3
	v_add_f32_e32 v3, v24, v25
	v_pk_add_f32 v[6:7], v[6:7], v[12:13]
	v_add_f32_e32 v14, v14, v15
	v_exp_f32_e32 v15, v3
	v_mov_b32_e32 v3, v6
	v_mov_b32_e32 v8, v6
	s_nop 1
	v_permlane32_swap_b32_e32 v3, v8
	v_cndmask_b32_e64 v8, v3, v8, s[0:1]
	v_pk_add_f32 v[190:191], v[6:7], v[8:9]
	v_cndmask_b32_e64 v6, 0, v8, s[0:1]
	v_add_f32_e32 v3, v182, v191
	v_add_f32_e32 v21, v4, v5
	v_mov_b32_e32 v4, v11
	v_mov_b32_e32 v5, v17
	v_add_f32_e32 v3, v6, v3
	v_pk_add_f32 v[4:5], v[2:3], v[4:5] neg_lo:[0,1] neg_hi:[0,1]
	v_mov_b32_e32 v17, v11
	v_mov_b32_e32 v6, v1
	v_mov_b32_e32 v7, v5
	v_pk_add_f32 v[6:7], v[6:7], v[16:17] neg_lo:[0,1] neg_hi:[0,1]
	v_mov_b32_e32 v11, v16
	v_mov_b32_e32 v1, v7
	v_pk_add_f32 v[0:1], v[0:1], v[10:11] neg_lo:[0,1] neg_hi:[0,1]
	v_add_f32_e32 v2, v181, v3
	v_add_f32_e32 v3, v4, v5
	v_add_f32_e32 v4, v6, v7
	v_add_f32_e32 v0, v0, v1
	v_exp_f32_e32 v2, v2
	v_exp_f32_e32 v4, v4
	v_exp_f32_e32 v0, v0
	v_exp_f32_e32 v1, v3
	v_exp_f32_e32 v3, v21
	v_exp_f32_e32 v5, v14
	v_add_f32_e32 v16, v183, v27
	v_cvt_pk_bf16_f32 v184, v0, v4
	v_cvt_pk_bf16_f32 v185, v1, v2
	v_cvt_pk_bf16_f32 v186, v3, v15
	v_cvt_pk_bf16_f32 v187, v5, v20
	v_exp_f32_e32 v64, v16
	v_add_f32_e32 v16, v30, v31
	s_waitcnt lgkmcnt(0)
	v_mfma_f32_32x32x16_bf16 v[0:15], v[154:157], v[184:187], v[32:47]
	v_exp_f32_e32 v155, v16
	v_add_f32_e32 v16, v28, v29
	v_exp_f32_e32 v156, v16
	v_add_f32_e32 v154, v188, v189
	v_mfma_f32_32x32x16_bf16 v[16:31], v[150:153], v[184:187], v[48:63]
	v_exp_f32_e32 v151, v154
	v_exp_f32_e32 v152, v194
	v_exp_f32_e32 v153, v192
	v_cvt_pk_bf16_f32 v150, v156, v155
	ds_read_b64_tr_b16 v[156:157], v180 offset:3520
	ds_read_b64_tr_b16 v[154:155], v180 offset:2368
	v_cvt_pk_bf16_f32 v151, v151, v64
	v_cvt_pk_bf16_f32 v152, v152, v193
	v_cvt_pk_bf16_f32 v153, v153, v196
	v_add_f32_e32 v64, v190, v191
	v_add_f32_e32 v181, v182, v64
	v_mfma_f32_32x32x16_bf16 v[0:15], v[146:149], v[150:153], v[0:15]
	v_cmp_lt_f32_e32 vcc, s75, v181
	s_cmp_eq_u64 vcc, 0
	s_cselect_b64 s[8:9], -1, 0
	s_xor_b64 s[6:7], s[6:7], -1
	s_or_b64 s[8:9], s[6:7], s[8:9]
	s_add_i32 s16, s16, -2
	s_sub_i32 s15, s15, 64
	s_waitcnt lgkmcnt(0)
	v_mfma_f32_32x32x16_bf16 v[16:31], v[154:157], v[150:153], v[16:31]
	s_mov_b64 s[6:7], 0

; template <bool CLAMP>
; __device__ __forceinline__ void load_k(bf16x8 (&kf)[4], const bf16_t* kbase, int k0, int kst, const WaveCtx& c) {
;     int kp = k0 + kst * c.q; if (CLAMP) kp = kp < 0 ? 0 : (kp > SEQ - 1 ? SEQ - 1 : kp);
;     const bf16_t* kr = kbase + (size_t)kp * LDQ + 8 * c.h;
; #pragma unroll
;     for (int ks = 0; ks < 4; ++ks) kf[ks] = *(const bf16x8*)(kr + 16 * ks);
; }
; template <bool CLAMP>
; __device__ __forceinline__ void load_v(u32x4 (&vr)[4], const bf16_t* vbase, int k0, int kst, const WaveCtx& c) {
; #pragma unroll
;     for (int i = 0; i < 4; ++i) { const int p = c.lane + 64 * i, n = p >> 3; int kp = k0 + kst * n; if (CLAMP) kp = kp < 0 ? 0 : (kp > SEQ - 1 ? SEQ - 1 : kp);
;         vr[i] = *(const u32x4*)(vbase + (size_t)kp * LDQ + (p & 7) * 8); }
; __device__ __forceinline__ void unit_C(const bf16_t* qkv, bf16_t* outC, int b, int hc, int qt, const WaveCtx& c) {
;     ...
;     for (int ch = qt; ch >= 0; ch -= 2) {
;         if (ch > 0) issue_kv<false>(tb, kbase, vbase, 32 * (ch - 1), 1, c);
;         C_STEP(ta, ch);
.LBB0_595:
	s_add_i32 s17, s14, s16
	s_cmp_eq_u32 s17, 0
	s_cselect_b64 s[6:7], -1, 0
	s_and_b64 vcc, exec, s[6:7]
	s_mov_b32 s18, 0
	s_cbranch_vccnz .LBB0_597
	v_add_u32_e32 v32, s15, v173
	v_mad_i64_i32 v[32:33], s[8:9], v32, s71, v[160:161]
	v_add_u32_e32 v36, s15, v169
	global_load_dwordx4 v[114:117], v[32:33], off
	global_load_dwordx4 v[118:121], v[32:33], off offset:32
	global_load_dwordx4 v[122:125], v[32:33], off offset:64
	global_load_dwordx4 v[126:129], v[32:33], off offset:96
	v_add_u32_e32 v32, 0x6e0, v36
	v_mad_i64_i32 v[32:33], s[8:9], v32, s71, v[162:163]
	v_add_u32_e32 v34, 0x6e8, v36
	v_mad_i64_i32 v[34:35], s[8:9], v34, s71, v[162:163]
	global_load_dwordx4 v[130:133], v[32:33], off
	global_load_dwordx4 v[134:137], v[34:35], off
	v_add_u32_e32 v32, 0x6f0, v36
	v_mad_i64_i32 v[32:33], s[8:9], v32, s71, v[162:163]
	v_add_u32_e32 v34, 0x6f8, v36
	v_mad_i64_i32 v[34:35], s[8:9], v34, s71, v[162:163]
	global_load_dwordx4 v[138:141], v[32:33], off
	global_load_dwordx4 v[142:145], v[34:35], off
	s_add_i32 s18, s15, 0x700
	s_waitcnt vmcnt(8) lgkmcnt(0)
	s_branch .Lgo_597

.Lgo_597:
	v_mfma_f32_32x32x16_bf16 v[32:47], v[82:85], v[66:69], 0
	s_cmp_lg_u32 s16, 0
	s_cselect_b64 s[8:9], -1, 0
	v_add_u32_e32 v64, v159, v158
	ds_write_b128 v64, v[98:101]
	ds_write_b128 v177, v[102:105]
	ds_write_b128 v178, v[106:109]
	ds_write_b128 v179, v[110:113]
	v_add_u32_e32 v180, s10, v175
	ds_read_b64_tr_b16 v[154:155], v180
	ds_read_b64_tr_b16 v[156:157], v180 offset:1152
	ds_read_b64_tr_b16 v[152:153], v180 offset:1216
	ds_read_b64_tr_b16 v[150:151], v180 offset:64
	ds_read_b64_tr_b16 v[146:147], v180 offset:2304
	ds_read_b64_tr_b16 v[148:149], v180 offset:3456
	v_mfma_f32_32x32x16_bf16 v[48:63], v[90:93], v[74:77], 0
	v_mfma_f32_32x32x16_bf16 v[32:47], v[86:89], v[70:73], v[32:47]
	v_mfma_f32_32x32x16_bf16 v[48:63], v[94:97], v[78:81], v[48:63]
	s_nop 11
	v_pk_add_f32 v[32:33], v[32:33], v[48:49]
	v_pk_add_f32 v[34:35], v[34:35], v[50:51]
	v_exp_f32_e64 v48, -|v32|
	v_max_f32_e32 v50, 0, v32
	v_or_b32_e32 v49, s18, v164
	v_cmp_lt_i32_e32 vcc, v49, v165
	v_add_f32_e32 v48, 1.0, v48
	v_log_f32_e32 v48, v48
	s_or_b64 vcc, s[8:9], vcc
	v_pk_add_f32 v[36:37], v[36:37], v[52:53]
	v_pk_add_f32 v[38:39], v[38:39], v[54:55]
	v_add_f32_e32 v48, v50, v48
	v_exp_f32_e64 v50, -|v33|
	v_sub_f32_e32 v32, v32, v48
	v_cndmask_b32_e32 v52, v244, v32, vcc
	v_cndmask_b32_e64 v51, 0, -v48, vcc
	v_add_f32_e32 v32, 1.0, v50
	v_log_f32_e32 v32, v32
	v_or_b32_e32 v48, 1, v49
	v_cmp_lt_i32_e32 vcc, v48, v165
	v_max_f32_e32 v48, 0, v33
	v_add_f32_e32 v32, v48, v32
	v_exp_f32_e64 v48, -|v34|
	s_or_b64 vcc, s[8:9], vcc
	v_cndmask_b32_e64 v50, 0, -v32, vcc
	v_sub_f32_e32 v32, v33, v32
	v_cndmask_b32_e32 v53, v244, v32, vcc
	v_add_f32_e32 v32, 1.0, v48
	v_log_f32_e32 v32, v32
	v_or_b32_e32 v33, 2, v49
	v_cmp_lt_i32_e32 vcc, v33, v165
	v_max_f32_e32 v33, 0, v34
	v_add_f32_e32 v32, v33, v32
	v_exp_f32_e64 v33, -|v35|
	s_or_b64 vcc, s[8:9], vcc
	v_cndmask_b32_e64 v54, 0, -v32, vcc
	v_sub_f32_e32 v32, v34, v32
	v_cndmask_b32_e32 v55, v244, v32, vcc
	v_add_f32_e32 v32, 1.0, v33
	v_log_f32_e32 v32, v32
	v_or_b32_e32 v33, 3, v49
	v_cmp_lt_i32_e32 vcc, v33, v165
	v_max_f32_e32 v33, 0, v35
	v_add_f32_e32 v32, v33, v32
	v_exp_f32_e64 v33, -|v36|
	s_or_b64 vcc, s[8:9], vcc
	v_pk_add_f32 v[40:41], v[40:41], v[56:57]
	v_cndmask_b32_e64 v56, 0, -v32, vcc
	v_sub_f32_e32 v32, v35, v32
	v_cndmask_b32_e32 v57, v244, v32, vcc
	v_add_f32_e32 v32, 1.0, v33
	v_log_f32_e32 v32, v32
	v_or_b32_e32 v33, 8, v49
	v_cmp_lt_i32_e32 vcc, v33, v165
	v_max_f32_e32 v33, 0, v36
	v_add_f32_e32 v32, v33, v32
	v_exp_f32_e64 v33, -|v37|
	s_or_b64 vcc, s[8:9], vcc
	v_cndmask_b32_e64 v35, 0, -v32, vcc
	v_sub_f32_e32 v32, v36, v32
	v_cndmask_b32_e32 v48, v244, v32, vcc
	v_add_f32_e32 v32, 1.0, v33
	v_log_f32_e32 v32, v32
	v_or_b32_e32 v33, 9, v49
	v_cmp_lt_i32_e32 vcc, v33, v165
	v_max_f32_e32 v33, 0, v37
	v_add_f32_e32 v32, v33, v32
	v_exp_f32_e64 v33, -|v38|
	s_or_b64 vcc, s[8:9], vcc
	v_pk_add_f32 v[42:43], v[42:43], v[58:59]
	v_cndmask_b32_e64 v58, 0, -v32, vcc
	v_sub_f32_e32 v32, v37, v32
	v_cndmask_b32_e32 v37, v244, v32, vcc
	v_add_f32_e32 v32, 1.0, v33
	v_log_f32_e32 v32, v32
	v_or_b32_e32 v33, 10, v49
	v_cmp_lt_i32_e32 vcc, v33, v165
	v_max_f32_e32 v33, 0, v38
	v_add_f32_e32 v32, v33, v32
	v_exp_f32_e64 v33, -|v39|
	s_or_b64 vcc, s[8:9], vcc
	v_cndmask_b32_e64 v59, 0, -v32, vcc
	v_sub_f32_e32 v32, v38, v32
	v_pk_add_f32 v[44:45], v[44:45], v[60:61]
	v_cndmask_b32_e32 v60, v244, v32, vcc
	v_add_f32_e32 v32, 1.0, v33
	v_log_f32_e32 v32, v32
	v_or_b32_e32 v33, 11, v49
	v_cmp_lt_i32_e32 vcc, v33, v165
	v_max_f32_e32 v33, 0, v39
	v_add_f32_e32 v32, v33, v32
	v_exp_f32_e64 v33, -|v40|
	s_or_b64 vcc, s[8:9], vcc
	v_cndmask_b32_e64 v61, 0, -v32, vcc
	v_sub_f32_e32 v32, v39, v32
	v_pk_add_f32 v[46:47], v[46:47], v[62:63]
	v_cndmask_b32_e32 v62, v244, v32, vcc
	v_add_f32_e32 v32, 1.0, v33
	v_log_f32_e32 v32, v32
	v_or_b32_e32 v33, 16, v49
	v_exp_f32_e64 v34, -|v41|
	v_cmp_lt_i32_e32 vcc, v33, v165
	v_max_f32_e32 v33, 0, v40
	v_add_f32_e32 v33, v33, v32
	s_or_b64 vcc, s[8:9], vcc
	v_cndmask_b32_e64 v32, 0, -v33, vcc
	v_sub_f32_e32 v33, v40, v33
	v_cndmask_b32_e32 v63, v244, v33, vcc
	v_add_f32_e32 v33, 1.0, v34
	v_log_f32_e32 v33, v33
	v_or_b32_e32 v34, 17, v49
	v_exp_f32_e64 v36, -|v42|
	v_cmp_lt_i32_e32 vcc, v34, v165
	v_max_f32_e32 v34, 0, v41
	v_add_f32_e32 v33, v34, v33
	s_or_b64 vcc, s[8:9], vcc
	v_cndmask_b32_e64 v34, 0, -v33, vcc
	v_sub_f32_e32 v33, v41, v33
	v_cndmask_b32_e32 v182, v244, v33, vcc
	v_add_f32_e32 v33, 1.0, v36
	v_log_f32_e32 v33, v33
	v_or_b32_e32 v36, 18, v49
	v_cmp_lt_i32_e32 vcc, v36, v165
	v_max_f32_e32 v36, 0, v42
	v_add_f32_e32 v33, v36, v33
	v_exp_f32_e64 v36, -|v43|
	s_or_b64 vcc, s[8:9], vcc
	v_cndmask_b32_e64 v39, 0, -v33, vcc
	v_sub_f32_e32 v33, v42, v33
	v_cndmask_b32_e32 v183, v244, v33, vcc
	v_add_f32_e32 v33, 1.0, v36
	v_log_f32_e32 v33, v33
	v_or_b32_e32 v36, 19, v49
	v_cmp_lt_i32_e32 vcc, v36, v165
	v_max_f32_e32 v36, 0, v43
	v_add_f32_e32 v33, v36, v33
	v_exp_f32_e64 v36, -|v44|
	s_or_b64 vcc, s[8:9], vcc
	v_cndmask_b32_e64 v184, 0, -v33, vcc
	v_sub_f32_e32 v33, v43, v33
	v_cndmask_b32_e32 v43, v244, v33, vcc
	v_add_f32_e32 v33, 1.0, v36
	v_log_f32_e32 v33, v33
	v_or_b32_e32 v36, 24, v49
	v_cmp_lt_i32_e32 vcc, v36, v165
	v_max_f32_e32 v36, 0, v44
	v_add_f32_e32 v33, v36, v33
	v_exp_f32_e64 v36, -|v45|
	s_or_b64 vcc, s[8:9], vcc
	v_cndmask_b32_e64 v41, 0, -v33, vcc
	v_sub_f32_e32 v33, v44, v33
	v_cndmask_b32_e32 v185, v244, v33, vcc
	v_add_f32_e32 v33, 1.0, v36
	v_log_f32_e32 v33, v33
	v_or_b32_e32 v36, 25, v49
	v_cmp_lt_i32_e32 vcc, v36, v165
	v_max_f32_e32 v36, 0, v45
	v_add_f32_e32 v33, v36, v33
	v_exp_f32_e64 v36, -|v46|
	s_or_b64 vcc, s[8:9], vcc
; __device__ __forceinline__ void unit_C(const bf16_t* qkv, bf16_t* outC, int b, int hc, int qt, const WaveCtx& c) {
;     ...
;     for (int ch = qt; ch >= 0; ch -= 2) {
;         if (ch > 0) issue_kv<false>(tb, kbase, vbase, 32 * (ch - 1), 1, c);
;         C_STEP(ta, ch);
;         if (done || ch == 0) break;
;         if (ch > 1) issue_kv<false>(ta, kbase, vbase, 32 * (ch - 2), 1, c);
;         C_STEP(tb, ch - 1);
	v_cndmask_b32_e64 v186, 0, -v33, vcc
	v_sub_f32_e32 v33, v45, v33
	v_cndmask_b32_e32 v45, v244, v33, vcc
	v_add_f32_e32 v33, 1.0, v36
	v_log_f32_e32 v33, v33
	v_or_b32_e32 v36, 26, v49
	v_cmp_lt_i32_e32 vcc, v36, v165
	v_max_f32_e32 v36, 0, v46
	v_add_f32_e32 v33, v36, v33
	v_exp_f32_e64 v36, -|v47|
	s_or_b64 vcc, s[8:9], vcc
	v_cndmask_b32_e64 v187, 0, -v33, vcc
	v_sub_f32_e32 v33, v46, v33
	v_cndmask_b32_e32 v46, v244, v33, vcc
	v_add_f32_e32 v33, 1.0, v36
	v_log_f32_e32 v33, v33
	v_or_b32_e32 v36, 27, v49
	v_cmp_lt_i32_e32 vcc, v36, v165
	v_max_f32_e32 v36, 0, v47
	v_add_f32_e32 v33, v36, v33
	s_or_b64 vcc, s[8:9], vcc
	v_cndmask_b32_e64 v49, 0, -v33, vcc
	v_sub_f32_e32 v33, v47, v33
	v_cndmask_b32_e32 v47, v244, v33, vcc
	v_add_f32_e32 v33, v51, v50
	v_add_f32_e32 v36, v54, v56
	v_add_f32_e32 v36, v33, v36
	v_add_f32_e32 v33, v35, v58
	v_add_f32_e32 v35, v59, v61
	v_add_f32_e32 v38, v33, v35
	v_add_f32_e32 v33, v41, v186
	v_mov_b32_e32 v41, v36
	v_mov_b32_e32 v42, v36
	s_nop 1
	v_permlane32_swap_b32_e32 v41, v42
	v_add_f32_e32 v35, v187, v49
	v_cndmask_b32_e64 v42, v41, v42, s[0:1]
	v_mov_b32_e32 v41, v38
	v_mov_b32_e32 v44, v38
	s_nop 1
	v_permlane32_swap_b32_e32 v41, v44
	v_pk_add_f32 v[32:33], v[32:33], v[34:35]
	v_cndmask_b32_e64 v44, v41, v44, s[0:1]
	v_mov_b32_e32 v35, v33
	v_mov_b32_e32 v41, v33
	s_nop 1
	v_permlane32_swap_b32_e32 v35, v41
	v_add_f32_e32 v40, v39, v184
	v_cndmask_b32_e64 v41, v35, v41, s[0:1]
	v_pk_add_f32 v[32:33], v[32:33], v[40:41]
	v_add_f32_e32 v51, 0, v181
	v_mov_b32_e32 v35, v32
	v_mov_b32_e32 v40, v32
	s_nop 1
	v_permlane32_swap_b32_e32 v35, v40
	v_cndmask_b32_e64 v64, v35, v40, s[0:1]
	v_cndmask_b32_e64 v35, 0, v41, s[0:1]
	v_add_f32_e32 v35, v51, v35
	v_add_f32_e32 v40, v49, v35
	v_add_f32_e32 v41, v187, v40
	v_add_f32_e32 v35, v47, v35
	v_exp_f32_e32 v47, v35
	v_add_f32_e32 v35, v45, v41
	v_pk_add_f32 v[32:33], v[32:33], v[64:65]
	v_add_f32_e32 v49, v186, v41
	v_exp_f32_e32 v41, v35
	v_add_f32_e32 v35, v181, v33
	v_cndmask_b32_e64 v45, 0, v64, s[0:1]
	v_add_f32_e32 v35, v45, v35
	v_add_f32_e32 v51, v184, v35
	v_add_f32_e32 v64, v39, v51
	v_mov_b32_e32 v39, v32
	v_mov_b32_e32 v45, v33
	v_pk_add_f32 v[32:33], v[38:39], v[44:45]
	v_add_f32_e32 v40, v46, v40
	v_add_f32_e32 v46, v185, v49
	v_add_f32_e32 v184, v34, v64
	v_add_f32_e32 v185, v43, v35
	v_cndmask_b32_e64 v34, 0, v44, s[0:1]
	v_add_f32_e32 v35, v181, v33
	v_add_f32_e32 v34, v34, v35
	v_add_f32_e32 v35, v61, v34
	v_add_f32_e32 v38, v59, v35
	v_add_f32_e32 v34, v62, v34
	v_add_f32_e32 v39, v58, v38
	v_exp_f32_e32 v44, v34
	v_add_f32_e32 v34, v60, v35
	v_add_f32_e32 v35, v37, v38
	v_mov_b32_e32 v37, v32
	v_mov_b32_e32 v43, v33
	v_add_f32_e32 v38, v48, v39
	v_pk_add_f32 v[48:49], v[36:37], v[42:43]
	v_cndmask_b32_e64 v39, 0, v42, s[0:1]
	v_add_f32_e32 v32, v181, v49
	v_add_f32_e32 v32, v39, v32
	v_add_f32_e32 v33, v56, v32
	v_add_f32_e32 v36, v54, v33
	v_add_f32_e32 v37, v50, v36
	v_add_f32_e32 v32, v57, v32
	v_exp_f32_e32 v39, v32
	v_add_f32_e32 v32, v55, v33
	v_add_f32_e32 v33, v53, v36
	v_add_f32_e32 v36, v52, v37
	v_exp_f32_e32 v35, v35
	v_exp_f32_e32 v33, v33
	v_exp_f32_e32 v36, v36
	v_exp_f32_e32 v37, v32
	v_exp_f32_e32 v38, v38
	v_exp_f32_e32 v42, v34
	v_cvt_pk_bf16_f32 v32, v36, v33
	v_cvt_pk_bf16_f32 v33, v37, v39
	v_cvt_pk_bf16_f32 v34, v38, v35
	v_cvt_pk_bf16_f32 v35, v42, v44
	v_add_f32_e32 v37, v183, v51
	v_add_f32_e32 v38, v182, v64
	s_waitcnt lgkmcnt(4)
	v_mfma_f32_32x32x16_bf16 v[0:15], v[154:157], v[32:35], v[0:15]
	v_add_f32_e32 v39, v63, v184
	v_exp_f32_e32 v36, v185
	v_exp_f32_e32 v37, v37
	v_exp_f32_e32 v38, v38
	v_exp_f32_e32 v39, v39
	s_waitcnt lgkmcnt(2)
	v_mfma_f32_32x32x16_bf16 v[16:31], v[150:153], v[32:35], v[16:31]
	v_exp_f32_e32 v32, v46
	v_exp_f32_e32 v33, v40
	v_cvt_pk_bf16_f32 v150, v39, v38
	v_cvt_pk_bf16_f32 v151, v37, v36
	v_cvt_pk_bf16_f32 v152, v32, v41
	v_cvt_pk_bf16_f32 v153, v33, v47
	v_mov_b64_e32 v[46:47], v[14:15]
	v_mov_b64_e32 v[44:45], v[12:13]
	v_mov_b64_e32 v[42:43], v[10:11]
	v_mov_b64_e32 v[40:41], v[8:9]
	v_mov_b64_e32 v[38:39], v[6:7]
	v_mov_b64_e32 v[36:37], v[4:5]
	v_mov_b64_e32 v[34:35], v[2:3]
	v_mov_b64_e32 v[32:33], v[0:1]
	ds_read_b64_tr_b16 v[2:3], v180 offset:3520
	ds_read_b64_tr_b16 v[0:1], v180 offset:2368
	v_add_f32_e32 v4, v48, v49
	v_mov_b64_e32 v[62:63], v[30:31]
	v_mov_b64_e32 v[60:61], v[28:29]
	v_mov_b64_e32 v[58:59], v[26:27]
	v_mov_b64_e32 v[56:57], v[24:25]
	v_mov_b64_e32 v[54:55], v[22:23]
	v_mov_b64_e32 v[52:53], v[20:21]
	v_mov_b64_e32 v[50:51], v[18:19]
	v_mov_b64_e32 v[48:49], v[16:17]
	s_waitcnt lgkmcnt(2)
	v_mfma_f32_32x32x16_bf16 v[32:47], v[146:149], v[150:153], v[32:47]
	v_add_f32_e32 v182, v181, v4
	v_cmp_lt_f32_e32 vcc, s75, v182
	s_cmp_eq_u64 vcc, 0
	s_cselect_b64 s[8:9], -1, 0
	s_or_b64 s[8:9], s[6:7], s[8:9]
	s_mov_b64 s[6:7], -1
	s_and_b64 vcc, exec, s[8:9]
	s_waitcnt lgkmcnt(0)
	v_mfma_f32_32x32x16_bf16 v[48:63], v[0:3], v[150:153], v[48:63]
	s_mov_b64 s[8:9], -1
	s_cbranch_vccnz .LBB0_594
	s_cmp_gt_u32 s17, 1
	s_cselect_b64 s[6:7], -1, 0
	s_cmp_lt_u32 s17, 2
	s_cbranch_scc1 .LBB0_593
	s_sub_i32 s17, s18, 64
	v_or_b32_e32 v0, s17, v174
	v_mad_i64_i32 v[0:1], s[8:9], v0, s71, v[160:161]
	global_load_dwordx4 v[82:85], v[0:1], off
	global_load_dwordx4 v[86:89], v[0:1], off offset:32
	global_load_dwordx4 v[90:93], v[0:1], off offset:64
	global_load_dwordx4 v[94:97], v[0:1], off offset:96
	v_or_b32_e32 v0, s17, v169
	v_mad_i64_i32 v[0:1], s[8:9], v0, s71, v[162:163]
	v_or_b32_e32 v2, s17, v170
	v_mad_i64_i32 v[2:3], s[8:9], v2, s71, v[162:163]
	global_load_dwordx4 v[98:101], v[0:1], off
	global_load_dwordx4 v[102:105], v[2:3], off
	v_or_b32_e32 v0, s17, v171
	v_mad_i64_i32 v[0:1], s[8:9], v0, s71, v[162:163]
	v_or_b32_e32 v2, s17, v172
	v_mad_i64_i32 v[2:3], s[8:9], v2, s71, v[162:163]
	global_load_dwordx4 v[106:109], v[0:1], off
	global_load_dwordx4 v[110:113], v[2:3], off
	s_waitcnt vmcnt(8)
	s_branch .Lgo_593
